# v7 + sample row of the even-layer mixers: the 32 LDS reads of each dot-product section issued at once into spare registers (the compiler waited for each read)
# baseline (speedup 1.0000x reference)
; #define LAS __attribute__((address_space(3)))
; __device__ __forceinline__ void sample_mix_even(Frame& F0, int j, int b) {
;     ...
;     for (int k = 0; k < 2; ++k) {
;         const int c = tid + 512 * k, g = c >> 8, win = 2 << g; const float xa = z[c];
;         const float* st = FIN(3) + ((size_t)(j * 128 + b) * 15) * 1024 + c;
;         float sr[15];
; #pragma unroll
;         for (int r = 0; r < 15; ++r) sr[r] = st[(size_t)r * 1024];
;         float s = xa;
; #pragma unroll
;         for (int r = 0; r < 15; ++r) s += (r >= 16 - win) ? sr[r] : 0.f;
;         pl[c] = s / (float)win - xa;
;         float* po = F.out + O_POOLS + ((size_t)(j * 128 + b) * 15) * 1024 + c;
; #pragma unroll
;         for (int r = 0; r < 14; ++r) po[(size_t)r * 1024] = sr[r + 1];
;         po[(size_t)14 * 1024] = xa;
;     }
;     __syncthreads();
;     ...
;         const bf16_t* pm = ((bf16_t*)(F.ws + WS_PMT)) + (size_t)(j * 4 + g) * 65536 + (size_t)dd * 256; const LAS float* pg = pl + g * 256;
.LBB0_1602:
	s_or_b64 exec, exec, s[4:5]
	v_cmp_lt_i32_e32 vcc, 14, v13
	s_waitcnt vmcnt(0)
	v_add_f32_e32 v28, v27, v28
	v_readlane_b32 s24, v254, 49
	v_cndmask_b32_e32 v0, 0, v31, vcc
	v_cmp_lt_i32_e32 vcc, 13, v13
	v_add_f32_e32 v0, v0, v28
	v_add_u32_e32 v54, s24, v26
	v_cndmask_b32_e32 v1, 0, v30, vcc
	v_cmp_lt_i32_e32 vcc, 12, v13
	v_add_f32_e32 v0, v1, v0
	v_ashrrev_i32_e32 v55, 31, v54
	v_cndmask_b32_e32 v14, 0, v29, vcc
	v_cmp_lt_i32_e32 vcc, 11, v13
	v_add_f32_e32 v0, v14, v0
	v_readlane_b32 s25, v254, 50
	v_cndmask_b32_e32 v15, 0, v8, vcc
	v_cmp_lt_i32_e32 vcc, 10, v13
	v_add_f32_e32 v0, v15, v0
	s_nop 0
	v_cndmask_b32_e32 v16, 0, v7, vcc
	v_cmp_lt_i32_e32 vcc, 9, v13
	v_add_f32_e32 v0, v16, v0
	s_nop 0
	v_cndmask_b32_e32 v17, 0, v6, vcc
	v_cmp_lt_i32_e32 vcc, 8, v13
	v_add_f32_e32 v0, v17, v0
	s_nop 0
	v_cndmask_b32_e32 v18, 0, v5, vcc
	v_cmp_lt_i32_e32 vcc, 7, v13
	v_add_f32_e32 v0, v18, v0
	s_nop 0
	v_cndmask_b32_e32 v19, 0, v4, vcc
	v_cmp_lt_i32_e32 vcc, 6, v13
	v_add_f32_e32 v0, v19, v0
	s_nop 0
	v_cndmask_b32_e32 v20, 0, v3, vcc
	v_cmp_lt_i32_e32 vcc, 5, v13
	v_add_f32_e32 v0, v20, v0
	s_nop 0
	v_cndmask_b32_e32 v21, 0, v2, vcc
	v_cmp_lt_i32_e32 vcc, 4, v13
	v_add_f32_e32 v0, v21, v0
	s_nop 0
	v_cndmask_b32_e32 v22, 0, v10, vcc
	v_cmp_lt_i32_e32 vcc, 3, v13
	v_add_f32_e32 v0, v22, v0
	s_nop 0
	v_cndmask_b32_e32 v23, 0, v9, vcc
	v_cmp_lt_i32_e32 vcc, 2, v13
	v_add_f32_e32 v0, v23, v0
	s_nop 0
	v_cndmask_b32_e32 v32, 0, v11, vcc
	v_cmp_lt_i32_e32 vcc, 1, v13
	v_cvt_f32_i32_e32 v13, v13
	v_add_f32_e32 v0, v32, v0
	v_cndmask_b32_e32 v34, 0, v12, vcc
	v_add_f32_e32 v14, v34, v0
	v_div_scale_f32 v15, s[4:5], v13, v13, v14
	v_rcp_f32_e32 v16, v15
	s_mov_b64 s[4:5], 0x4170000
	v_lshl_add_u64 v[0:1], v[24:25], 0, s[4:5]
	s_mov_b32 s4, 0x8000
	v_fma_f32 v17, -v15, v16, 1.0
	v_fmac_f32_e32 v16, v17, v16
	v_div_scale_f32 v17, vcc, v14, v13, v14
	v_mul_f32_e32 v18, v17, v16
	v_fma_f32 v19, -v15, v18, v17
	v_fmac_f32_e32 v18, v19, v16
	v_fma_f32 v15, -v15, v18, v17
	v_div_fmas_f32 v15, v15, v16, v18
	v_div_fixup_f32 v13, v15, v13, v14
	v_add_co_u32_e32 v14, vcc, s33, v0
	global_store_dword v[0:1], v31, off offset:2048
	s_nop 0
	v_addc_co_u32_e32 v15, vcc, 0, v1, vcc
	global_store_dword v[14:15], v30, off offset:2048
	v_add_co_u32_e32 v14, vcc, s70, v0
	v_sub_f32_e32 v13, v13, v27
	s_nop 0
	v_addc_co_u32_e32 v15, vcc, 0, v1, vcc
	global_store_dword v[14:15], v29, off offset:2048
	v_add_co_u32_e32 v14, vcc, s95, v0
	ds_write_b32 v33, v13 offset:2048
	s_nop 0
	v_addc_co_u32_e32 v15, vcc, 0, v1, vcc
	global_store_dword v[14:15], v8, off offset:2048
	v_add_co_u32_e32 v14, vcc, s94, v0
	s_nop 1
	v_addc_co_u32_e32 v15, vcc, 0, v1, vcc
	global_store_dword v[14:15], v7, off offset:2048
	v_add_co_u32_e32 v14, vcc, s81, v0
	s_nop 1
	v_addc_co_u32_e32 v15, vcc, 0, v1, vcc
	global_store_dword v[14:15], v6, off offset:2048
	v_add_co_u32_e32 v6, vcc, s71, v0
	s_nop 1
	v_addc_co_u32_e32 v7, vcc, 0, v1, vcc
	global_store_dword v[6:7], v5, off offset:2048
	v_add_co_u32_e32 v6, vcc, s82, v0
	s_nop 1
	v_addc_co_u32_e32 v7, vcc, 0, v1, vcc
	global_store_dword v[6:7], v4, off offset:2048
	v_add_co_u32_e32 v4, vcc, s4, v0
	s_mov_b32 s4, 0x9000
	s_nop 0
	v_addc_co_u32_e32 v5, vcc, 0, v1, vcc
	global_store_dword v[4:5], v3, off offset:2048
	v_add_co_u32_e32 v4, vcc, s4, v0
	s_mov_b32 s4, 0xa000
	s_nop 0
	v_addc_co_u32_e32 v5, vcc, 0, v1, vcc
	global_store_dword v[4:5], v2, off offset:2048
	v_add_co_u32_e32 v2, vcc, s4, v0
	s_mov_b32 s4, 0xb000
	s_nop 0
	v_addc_co_u32_e32 v3, vcc, 0, v1, vcc
	global_store_dword v[2:3], v10, off offset:2048
	v_add_co_u32_e32 v2, vcc, s4, v0
	s_mov_b32 s4, 0xc000
	s_nop 0
	v_addc_co_u32_e32 v3, vcc, 0, v1, vcc
	global_store_dword v[2:3], v9, off offset:2048
	v_add_co_u32_e32 v2, vcc, s4, v0
	s_mov_b32 s4, 0xd000
	s_nop 0
	v_addc_co_u32_e32 v3, vcc, 0, v1, vcc
	global_store_dword v[2:3], v11, off offset:2048
	v_add_co_u32_e32 v2, vcc, s4, v0
	s_mov_b32 s4, 0xe000
	s_nop 0
	v_addc_co_u32_e32 v3, vcc, 0, v1, vcc
	v_add_co_u32_e32 v0, vcc, s4, v0
	s_mov_b64 s[4:5], 0x6600000
	s_nop 0
	v_addc_co_u32_e32 v1, vcc, 0, v1, vcc
	global_store_dword v[0:1], v27, off offset:2048
	v_lshlrev_b32_e32 v0, 9, v48
	v_and_b32_e32 v200, 0x1fe00, v0
	v_lshl_add_u64 v[0:1], s[12:13], 0, v[200:201]
	v_lshl_add_u64 v[52:53], v[0:1], 0, s[4:5]
	v_lshlrev_b64 v[0:1], 17, v[54:55]
	v_lshl_add_u64 v[56:57], v[52:53], 0, v[0:1]
	global_store_dword v[2:3], v12, off offset:2048
	s_waitcnt lgkmcnt(0)
	s_barrier
; #define LAS __attribute__((address_space(3)))
; __device__ __forceinline__ float dot4(f32x4 a, f32x4 b) { return (a[0] * b[0] + a[1] * b[1]) + (a[2] * b[2] + a[3] * b[3]); }
; __device__ __forceinline__ void unpack8(u32x4 w, f32x4& a, f32x4& b) { a = (f32x4){bflo(w.x), bfhi(w.x), bflo(w.y), bfhi(w.y)}; b = (f32x4){bflo(w.z), bfhi(w.z), bflo(w.w), bfhi(w.w)}; }
; __device__ __forceinline__ void sample_mix_even(Frame& F0, int j, int b) {
;     ...
;     float tot = 0.f;
; #pragma unroll
;     for (int i = 0; i < 8; ++i) tot += red[i];
;     const float rv = rsqrtf(tot * (1.0f / D) + EPS);
; #pragma unroll
;     for (int k = 0; k < 2; ++k) {
;         const int d = tid + 512 * k, g = d >> 8, dd = d & 255;
;         const bf16_t* pm = ((bf16_t*)(F.ws + WS_PMT)) + (size_t)(j * 4 + g) * 65536 + (size_t)dd * 256; const LAS float* pg = pl + g * 256;
;         float a = 0.f;
; #pragma unroll
;         for (int hb = 0; hb < 2; ++hb) {
;             u32x4 pr[16];
; #pragma unroll
;             for (int i = 0; i < 16; ++i) pr[i] = *(const u32x4*)(pm + hb * 128 + i * 8);
; #pragma unroll
;             for (int i = 0; i < 16; ++i) { f32x4 p0, p1; unpack8(pr[i], p0, p1); const LAS float* q = pg + hb * 128 + i * 8; a += dot4(p0, *(const LAS f32x4*)q) + dot4(p1, *(const LAS f32x4*)(q + 4)); }
	global_load_dwordx4 v[40:43], v[56:57], off
	global_load_dwordx4 v[44:47], v[56:57], off offset:16
	ds_read_b128 v[0:3], v201 offset:4096
	ds_read_b128 v[4:7], v201 offset:4112
	global_load_dwordx4 v[64:67], v[56:57], off offset:32
	global_load_dwordx4 v[68:71], v[56:57], off offset:48
	s_mov_b32 s4, 0x800000
	s_waitcnt lgkmcnt(1)
	v_add_f32_e32 v0, 0, v0
	v_add_f32_e32 v0, v0, v1
	v_add_f32_e32 v0, v0, v2
	v_add_f32_e32 v0, v0, v3
	s_waitcnt lgkmcnt(0)
	v_add_f32_e32 v0, v0, v4
	v_add_f32_e32 v0, v0, v5
	v_add_f32_e32 v0, v0, v6
	v_add_f32_e32 v0, v0, v7
	v_mov_b32_e32 v1, 0x358637bd
	v_fmamk_f32 v0, v0, 0x3a800000, v1
	v_cmp_gt_f32_e32 vcc, s4, v0
	v_mul_f32_e32 v1, 0x4b800000, v0
	s_load_dwordx8 s[4:11], s[14:15], 0x60
	v_cndmask_b32_e32 v0, v0, v1, vcc
	v_rsq_f32_e32 v0, v0
	s_lshl_b64 s[14:15], s[16:17], 12
	s_add_u32 s2, s2, s14
	s_addc_u32 s3, s3, s15
	v_mul_f32_e32 v1, 0x45800000, v0
	v_cndmask_b32_e32 v59, v0, v1, vcc
	v_and_b32_e32 v0, 0x3fffff00, v48
	v_lshl_add_u32 v63, v0, 2, 0
	global_load_dwordx4 v[32:35], v[56:57], off offset:112
	global_load_dwordx4 v[36:39], v[56:57], off offset:96
	global_load_dwordx4 v[72:75], v[56:57], off offset:80
	global_load_dwordx4 v[76:79], v[56:57], off offset:64
	global_load_dwordx4 v[16:19], v[56:57], off offset:176
	global_load_dwordx4 v[20:23], v[56:57], off offset:160
	global_load_dwordx4 v[24:27], v[56:57], off offset:144
	global_load_dwordx4 v[28:31], v[56:57], off offset:128
	global_load_dwordx4 v[0:3], v[56:57], off offset:240
	global_load_dwordx4 v[4:7], v[56:57], off offset:224
	global_load_dwordx4 v[8:11], v[56:57], off offset:208
	global_load_dwordx4 v[12:15], v[56:57], off offset:192
	ds_read_b128 v[102:105], v63
	ds_read_b128 v[106:109], v63 offset:16
	ds_read_b128 v[110:113], v63 offset:32
	ds_read_b128 v[114:117], v63 offset:48
	ds_read_b128 v[118:121], v63 offset:64
	ds_read_b128 v[122:125], v63 offset:80
	ds_read_b128 v[126:129], v63 offset:96
	ds_read_b128 v[130:133], v63 offset:112
	ds_read_b128 v[134:137], v63 offset:128
	ds_read_b128 v[138:141], v63 offset:144
	ds_read_b128 v[142:145], v63 offset:160
	ds_read_b128 v[146:149], v63 offset:176
	ds_read_b128 v[150:153], v63 offset:192
	ds_read_b128 v[154:157], v63 offset:208
	ds_read_b128 v[158:161], v63 offset:224
	ds_read_b128 v[162:165], v63 offset:240
	ds_read_b128 v[166:169], v63 offset:256
	ds_read_b128 v[170:173], v63 offset:272
	ds_read_b128 v[174:177], v63 offset:288
	ds_read_b128 v[178:181], v63 offset:304
	ds_read_b128 v[182:185], v63 offset:320
	ds_read_b128 v[186:189], v63 offset:336
	ds_read_b128 v[190:193], v63 offset:352
	ds_read_b128 v[194:197], v63 offset:368
	ds_read_b128 v[202:205], v63 offset:384
	ds_read_b128 v[206:209], v63 offset:400
	ds_read_b128 v[210:213], v63 offset:416
	ds_read_b128 v[214:217], v63 offset:432
	ds_read_b128 v[218:221], v63 offset:448
	ds_read_b128 v[222:225], v63 offset:464
	ds_read_b128 v[226:229], v63 offset:480
	ds_read_b128 v[230:233], v63 offset:496
	s_waitcnt lgkmcnt(0)
	s_lshl_b64 s[0:1], s[0:1], 12
	s_add_u32 s0, s12, s0
	s_addc_u32 s1, s13, s1
	s_add_i32 s93, s93, s22
	s_cmp_lt_i32 s93, 16
	s_waitcnt vmcnt(15)
	v_lshlrev_b32_e32 v92, 16, v40
	v_and_b32_e32 v93, 0xffff0000, v40
	v_lshlrev_b32_e32 v94, 16, v41
	v_and_b32_e32 v95, 0xffff0000, v41
	v_lshlrev_b32_e32 v96, 16, v42
	v_and_b32_e32 v97, 0xffff0000, v42
	v_lshlrev_b32_e32 v98, 16, v43
	v_and_b32_e32 v99, 0xffff0000, v43
	s_waitcnt lgkmcnt(0)
	v_mul_f32_e32 v81, v103, v93
	v_fmac_f32_e32 v81, v102, v92
	v_mul_f32_e32 v41, v107, v97
	v_fmac_f32_e32 v41, v106, v96
	v_mul_f32_e32 v40, v109, v99
	v_mul_f32_e32 v80, v105, v95
	v_fmac_f32_e32 v40, v108, v98
	s_waitcnt vmcnt(14)
	v_and_b32_e32 v42, 0xffff0000, v44
	v_fmac_f32_e32 v80, v104, v94
	v_add_f32_e32 v40, v41, v40
	v_lshlrev_b32_e32 v41, 16, v44
	v_and_b32_e32 v44, 0xffff0000, v45
	v_mul_f32_e32 v42, v111, v42
	v_add_f32_e32 v80, v81, v80
	v_lshlrev_b32_e32 v43, 16, v45
	v_fmac_f32_e32 v42, v110, v41
	v_mul_f32_e32 v41, v113, v44
	v_add_f32_e32 v40, v80, v40
	v_lshlrev_b32_e32 v45, 16, v46
	v_and_b32_e32 v46, 0xffff0000, v46
	v_lshlrev_b32_e32 v80, 16, v47
	v_and_b32_e32 v47, 0xffff0000, v47
	v_fmac_f32_e32 v41, v112, v43
	v_add_f32_e32 v41, v42, v41
	v_mul_f32_e32 v42, v115, v46
	v_mul_f32_e32 v43, v117, v47
	v_fmac_f32_e32 v42, v114, v45
	v_fmac_f32_e32 v43, v116, v80
	v_add_f32_e32 v42, v42, v43
	v_add_f32_e32 v40, 0, v40
	v_add_f32_e32 v41, v41, v42
	v_add_f32_e32 v80, v40, v41
	s_waitcnt vmcnt(13)
	v_and_b32_e32 v44, 0xffff0000, v64
	v_lshlrev_b32_e32 v81, 16, v64
	v_lshlrev_b32_e32 v64, 16, v65
	v_and_b32_e32 v65, 0xffff0000, v65
	s_waitcnt lgkmcnt(0)
	v_mul_f32_e32 v41, v119, v44
	v_fmac_f32_e32 v41, v118, v81
	v_mul_f32_e32 v40, v121, v65
	v_lshlrev_b32_e32 v82, 16, v66
	v_and_b32_e32 v66, 0xffff0000, v66
	v_lshlrev_b32_e32 v83, 16, v67
	v_and_b32_e32 v67, 0xffff0000, v67
	v_fmac_f32_e32 v40, v120, v64
	v_add_f32_e32 v40, v41, v40
	s_waitcnt lgkmcnt(0)
	v_mul_f32_e32 v41, v123, v66
	v_mul_f32_e32 v42, v125, v67
	v_fmac_f32_e32 v41, v122, v82
	v_fmac_f32_e32 v42, v124, v83
	v_add_f32_e32 v41, v41, v42
	v_add_f32_e32 v40, v40, v41
	v_add_f32_e32 v64, v80, v40
	s_waitcnt vmcnt(12)
	v_and_b32_e32 v44, 0xffff0000, v68
	v_lshlrev_b32_e32 v65, 16, v68
	v_and_b32_e32 v67, 0xffff0000, v69
	v_lshlrev_b32_e32 v66, 16, v69
	s_waitcnt lgkmcnt(0)
	v_mul_f32_e32 v41, v127, v44
	v_fmac_f32_e32 v41, v126, v65
	v_mul_f32_e32 v40, v129, v67
	v_lshlrev_b32_e32 v68, 16, v70
	v_and_b32_e32 v69, 0xffff0000, v70
	v_lshlrev_b32_e32 v70, 16, v71
	v_and_b32_e32 v71, 0xffff0000, v71
	v_fmac_f32_e32 v40, v128, v66
	v_add_f32_e32 v40, v41, v40
	s_waitcnt lgkmcnt(0)
; #define LAS __attribute__((address_space(3)))
; __device__ __forceinline__ float dot4(f32x4 a, f32x4 b) { return (a[0] * b[0] + a[1] * b[1]) + (a[2] * b[2] + a[3] * b[3]); }
; __device__ __forceinline__ void unpack8(u32x4 w, f32x4& a, f32x4& b) { a = (f32x4){bflo(w.x), bfhi(w.x), bflo(w.y), bfhi(w.y)}; b = (f32x4){bflo(w.z), bfhi(w.z), bflo(w.w), bfhi(w.w)}; }
; __device__ __forceinline__ void sample_mix_even(Frame& F0, int j, int b) {
;     ...
; #pragma unroll
;     for (int k = 0; k < 2; ++k) {
;         const int d = tid + 512 * k, g = d >> 8, dd = d & 255;
;         const bf16_t* pm = ((bf16_t*)(F.ws + WS_PMT)) + (size_t)(j * 4 + g) * 65536 + (size_t)dd * 256; const LAS float* pg = pl + g * 256;
;         float a = 0.f;
; #pragma unroll
;         for (int hb = 0; hb < 2; ++hb) {
;             u32x4 pr[16];
; #pragma unroll
;             for (int i = 0; i < 16; ++i) pr[i] = *(const u32x4*)(pm + hb * 128 + i * 8);
; #pragma unroll
;             for (int i = 0; i < 16; ++i) { f32x4 p0, p1; unpack8(pr[i], p0, p1); const LAS float* q = pg + hb * 128 + i * 8; a += dot4(p0, *(const LAS f32x4*)q) + dot4(p1, *(const LAS f32x4*)(q + 4)); }
;         }
	v_mul_f32_e32 v41, v131, v69
	v_mul_f32_e32 v42, v133, v71
	v_fmac_f32_e32 v41, v130, v68
	v_fmac_f32_e32 v42, v132, v70
	v_add_f32_e32 v41, v41, v42
	v_add_f32_e32 v40, v40, v41
	v_add_f32_e32 v64, v64, v40
	s_waitcnt vmcnt(8)
	v_and_b32_e32 v44, 0xffff0000, v76
	v_lshlrev_b32_e32 v65, 16, v76
	v_and_b32_e32 v67, 0xffff0000, v77
	v_lshlrev_b32_e32 v66, 16, v77
	s_waitcnt lgkmcnt(0)
	v_mul_f32_e32 v41, v135, v44
	v_fmac_f32_e32 v41, v134, v65
	v_mul_f32_e32 v40, v137, v67
	v_and_b32_e32 v69, 0xffff0000, v78
	v_and_b32_e32 v71, 0xffff0000, v79
	v_fmac_f32_e32 v40, v136, v66
	v_lshlrev_b32_e32 v68, 16, v78
	v_lshlrev_b32_e32 v70, 16, v79
	v_add_f32_e32 v40, v41, v40
	s_waitcnt lgkmcnt(0)
	v_mul_f32_e32 v41, v139, v69
	v_mul_f32_e32 v42, v141, v71
	v_fmac_f32_e32 v41, v138, v68
	v_fmac_f32_e32 v42, v140, v70
	v_add_f32_e32 v41, v41, v42
	v_add_f32_e32 v40, v40, v41
	v_add_f32_e32 v64, v64, v40
	v_and_b32_e32 v44, 0xffff0000, v72
	v_lshlrev_b32_e32 v65, 16, v72
	v_and_b32_e32 v67, 0xffff0000, v73
	v_lshlrev_b32_e32 v66, 16, v73
	s_waitcnt lgkmcnt(0)
	v_mul_f32_e32 v41, v143, v44
	v_fmac_f32_e32 v41, v142, v65
	v_mul_f32_e32 v40, v145, v67
	v_and_b32_e32 v69, 0xffff0000, v74
	v_and_b32_e32 v71, 0xffff0000, v75
	v_fmac_f32_e32 v40, v144, v66
	v_lshlrev_b32_e32 v68, 16, v74
	v_lshlrev_b32_e32 v70, 16, v75
	v_add_f32_e32 v40, v41, v40
	s_waitcnt lgkmcnt(0)
	v_mul_f32_e32 v41, v147, v69
	v_mul_f32_e32 v42, v149, v71
	v_fmac_f32_e32 v41, v146, v68
	v_fmac_f32_e32 v42, v148, v70
	v_add_f32_e32 v41, v41, v42
	v_add_f32_e32 v40, v40, v41
	v_add_f32_e32 v44, v64, v40
	v_lshlrev_b32_e32 v45, 16, v36
	v_and_b32_e32 v36, 0xffff0000, v36
	v_lshlrev_b32_e32 v46, 16, v37
	v_and_b32_e32 v47, 0xffff0000, v37
	v_lshlrev_b32_e32 v64, 16, v38
	v_and_b32_e32 v65, 0xffff0000, v38
	v_lshlrev_b32_e32 v66, 16, v39
	v_and_b32_e32 v67, 0xffff0000, v39
	s_waitcnt lgkmcnt(0)
	v_mul_f32_e32 v41, v151, v36
	v_fmac_f32_e32 v41, v150, v45
	v_mul_f32_e32 v40, v153, v47
	v_fmac_f32_e32 v40, v152, v46
	v_add_f32_e32 v40, v41, v40
	s_waitcnt lgkmcnt(0)
	v_mul_f32_e32 v37, v155, v65
	v_fmac_f32_e32 v37, v154, v64
	v_mul_f32_e32 v36, v157, v67
	v_fmac_f32_e32 v36, v156, v66
	v_add_f32_e32 v36, v37, v36
	v_add_f32_e32 v36, v40, v36
	v_add_f32_e32 v40, v44, v36
	v_lshlrev_b32_e32 v41, 16, v32
	v_and_b32_e32 v32, 0xffff0000, v32
	v_lshlrev_b32_e32 v42, 16, v33
	v_and_b32_e32 v43, 0xffff0000, v33
	v_lshlrev_b32_e32 v44, 16, v34
	v_and_b32_e32 v45, 0xffff0000, v34
	v_lshlrev_b32_e32 v46, 16, v35
	v_and_b32_e32 v47, 0xffff0000, v35
	s_waitcnt lgkmcnt(0)
	v_mul_f32_e32 v37, v159, v32
	v_fmac_f32_e32 v37, v158, v41
	v_mul_f32_e32 v36, v161, v43
	v_fmac_f32_e32 v36, v160, v42
	v_add_f32_e32 v36, v37, v36
	s_waitcnt lgkmcnt(0)
	v_mul_f32_e32 v33, v163, v45
	v_fmac_f32_e32 v33, v162, v44
	v_mul_f32_e32 v32, v165, v47
	v_fmac_f32_e32 v32, v164, v46
	v_add_f32_e32 v32, v33, v32
	v_add_f32_e32 v32, v36, v32
	v_add_f32_e32 v36, v40, v32
	s_waitcnt vmcnt(4)
	v_lshlrev_b32_e32 v37, 16, v28
	v_and_b32_e32 v28, 0xffff0000, v28
	v_lshlrev_b32_e32 v38, 16, v29
	v_and_b32_e32 v39, 0xffff0000, v29
	v_lshlrev_b32_e32 v40, 16, v30
	v_and_b32_e32 v41, 0xffff0000, v30
	v_lshlrev_b32_e32 v42, 16, v31
	v_and_b32_e32 v43, 0xffff0000, v31
	s_waitcnt lgkmcnt(0)
	v_mul_f32_e32 v33, v167, v28
	v_fmac_f32_e32 v33, v166, v37
	v_mul_f32_e32 v32, v169, v39
	v_fmac_f32_e32 v32, v168, v38
	v_add_f32_e32 v32, v33, v32
	s_waitcnt lgkmcnt(0)
	v_mul_f32_e32 v29, v171, v41
	v_fmac_f32_e32 v29, v170, v40
	v_mul_f32_e32 v28, v173, v43
	v_fmac_f32_e32 v28, v172, v42
	v_add_f32_e32 v28, v29, v28
	v_add_f32_e32 v28, v32, v28
	v_add_f32_e32 v32, v36, v28
	v_lshlrev_b32_e32 v33, 16, v24
	v_and_b32_e32 v24, 0xffff0000, v24
	v_lshlrev_b32_e32 v34, 16, v25
	v_and_b32_e32 v35, 0xffff0000, v25
	v_lshlrev_b32_e32 v36, 16, v26
	v_and_b32_e32 v37, 0xffff0000, v26
	v_lshlrev_b32_e32 v38, 16, v27
	v_and_b32_e32 v39, 0xffff0000, v27
	s_waitcnt lgkmcnt(0)
	v_mul_f32_e32 v29, v175, v24
	v_fmac_f32_e32 v29, v174, v33
	v_mul_f32_e32 v28, v177, v35
	v_fmac_f32_e32 v28, v176, v34
	v_add_f32_e32 v28, v29, v28
	s_waitcnt lgkmcnt(0)
	v_mul_f32_e32 v25, v179, v37
	v_fmac_f32_e32 v25, v178, v36
	v_mul_f32_e32 v24, v181, v39
	v_fmac_f32_e32 v24, v180, v38
	v_add_f32_e32 v24, v25, v24
	v_add_f32_e32 v24, v28, v24
	v_add_f32_e32 v28, v32, v24
	v_lshlrev_b32_e32 v29, 16, v20
	v_and_b32_e32 v20, 0xffff0000, v20
	v_lshlrev_b32_e32 v30, 16, v21
	v_and_b32_e32 v31, 0xffff0000, v21
	v_lshlrev_b32_e32 v32, 16, v22
	v_and_b32_e32 v33, 0xffff0000, v22
	v_lshlrev_b32_e32 v34, 16, v23
	v_and_b32_e32 v35, 0xffff0000, v23
	s_waitcnt lgkmcnt(0)
	v_mul_f32_e32 v25, v183, v20
	v_fmac_f32_e32 v25, v182, v29
	v_mul_f32_e32 v24, v185, v31
	v_fmac_f32_e32 v24, v184, v30
	v_add_f32_e32 v24, v25, v24
	s_waitcnt lgkmcnt(0)
	v_mul_f32_e32 v21, v187, v33
	v_fmac_f32_e32 v21, v186, v32
	v_mul_f32_e32 v20, v189, v35
	v_fmac_f32_e32 v20, v188, v34
	v_add_f32_e32 v20, v21, v20
	v_add_f32_e32 v20, v24, v20
	v_add_f32_e32 v24, v28, v20
	v_lshlrev_b32_e32 v25, 16, v16
	v_and_b32_e32 v16, 0xffff0000, v16
	v_lshlrev_b32_e32 v26, 16, v17
	v_and_b32_e32 v27, 0xffff0000, v17
	v_lshlrev_b32_e32 v28, 16, v18
	v_and_b32_e32 v29, 0xffff0000, v18
	v_lshlrev_b32_e32 v30, 16, v19
	v_and_b32_e32 v31, 0xffff0000, v19
	s_waitcnt lgkmcnt(0)
	v_mul_f32_e32 v21, v191, v16
	v_fmac_f32_e32 v21, v190, v25
	v_mul_f32_e32 v20, v193, v27
	v_fmac_f32_e32 v20, v192, v26
	v_add_f32_e32 v20, v21, v20
	s_waitcnt lgkmcnt(0)
	v_mul_f32_e32 v17, v195, v29
	v_fmac_f32_e32 v17, v194, v28
	v_mul_f32_e32 v16, v197, v31
	v_fmac_f32_e32 v16, v196, v30
	v_add_f32_e32 v16, v17, v16
	v_add_f32_e32 v16, v20, v16
	global_load_dwordx4 v[64:67], v[56:57], off offset:256
	v_add_f32_e32 v20, v24, v16
	s_waitcnt vmcnt(1)
; #define LAS __attribute__((address_space(3)))
; __device__ __forceinline__ float dot4(f32x4 a, f32x4 b) { return (a[0] * b[0] + a[1] * b[1]) + (a[2] * b[2] + a[3] * b[3]); }
; __device__ __forceinline__ void unpack8(u32x4 w, f32x4& a, f32x4& b) { a = (f32x4){bflo(w.x), bfhi(w.x), bflo(w.y), bfhi(w.y)}; b = (f32x4){bflo(w.z), bfhi(w.z), bflo(w.w), bfhi(w.w)}; }
; __device__ __forceinline__ void sample_mix_even(Frame& F0, int j, int b) {
;     ...
;         for (int hb = 0; hb < 2; ++hb) {
;             u32x4 pr[16];
; #pragma unroll
;             for (int i = 0; i < 16; ++i) pr[i] = *(const u32x4*)(pm + hb * 128 + i * 8);
; #pragma unroll
;             for (int i = 0; i < 16; ++i) { f32x4 p0, p1; unpack8(pr[i], p0, p1); const LAS float* q = pg + hb * 128 + i * 8; a += dot4(p0, *(const LAS f32x4*)q) + dot4(p1, *(const LAS f32x4*)(q + 4)); }
;         }
	v_lshlrev_b32_e32 v21, 16, v12
	v_and_b32_e32 v12, 0xffff0000, v12
	v_lshlrev_b32_e32 v22, 16, v13
	v_and_b32_e32 v23, 0xffff0000, v13
	v_lshlrev_b32_e32 v24, 16, v14
	v_and_b32_e32 v25, 0xffff0000, v14
	v_lshlrev_b32_e32 v26, 16, v15
	v_and_b32_e32 v27, 0xffff0000, v15
	s_waitcnt lgkmcnt(0)
	v_mul_f32_e32 v17, v203, v12
	v_fmac_f32_e32 v17, v202, v21
	v_mul_f32_e32 v16, v205, v23
	global_load_dwordx4 v[68:71], v[56:57], off offset:272
	v_fmac_f32_e32 v16, v204, v22
	s_waitcnt lgkmcnt(0)
	v_mul_f32_e32 v13, v207, v25
	v_fmac_f32_e32 v13, v206, v24
	v_mul_f32_e32 v12, v209, v27
	v_fmac_f32_e32 v12, v208, v26
	v_add_f32_e32 v16, v17, v16
	v_add_f32_e32 v12, v13, v12
	v_add_f32_e32 v12, v16, v12
	v_add_f32_e32 v16, v20, v12
	v_lshlrev_b32_e32 v17, 16, v8
	v_and_b32_e32 v8, 0xffff0000, v8
	v_lshlrev_b32_e32 v18, 16, v9
	v_and_b32_e32 v19, 0xffff0000, v9
	v_lshlrev_b32_e32 v20, 16, v10
	v_and_b32_e32 v21, 0xffff0000, v10
	v_lshlrev_b32_e32 v22, 16, v11
	v_and_b32_e32 v23, 0xffff0000, v11
	s_waitcnt lgkmcnt(0)
	v_mul_f32_e32 v13, v211, v8
	global_load_dwordx4 v[72:75], v[56:57], off offset:288
	v_fmac_f32_e32 v13, v210, v17
	v_mul_f32_e32 v12, v213, v19
	v_fmac_f32_e32 v12, v212, v18
	s_waitcnt lgkmcnt(0)
	v_mul_f32_e32 v9, v215, v21
	v_fmac_f32_e32 v9, v214, v20
	v_mul_f32_e32 v8, v217, v23
	v_fmac_f32_e32 v8, v216, v22
	v_add_f32_e32 v12, v13, v12
	v_add_f32_e32 v8, v9, v8
	v_add_f32_e32 v8, v12, v8
	v_add_f32_e32 v12, v16, v8
	v_lshlrev_b32_e32 v13, 16, v4
	v_and_b32_e32 v4, 0xffff0000, v4
	v_lshlrev_b32_e32 v14, 16, v5
	v_and_b32_e32 v15, 0xffff0000, v5
	v_lshlrev_b32_e32 v16, 16, v6
	v_and_b32_e32 v17, 0xffff0000, v6
	v_lshlrev_b32_e32 v18, 16, v7
	v_and_b32_e32 v19, 0xffff0000, v7
	s_waitcnt lgkmcnt(0)
	v_mul_f32_e32 v9, v219, v4
	global_load_dwordx4 v[44:47], v[56:57], off offset:304
	v_fmac_f32_e32 v9, v218, v13
	v_mul_f32_e32 v8, v221, v15
	v_fmac_f32_e32 v8, v220, v14
	s_waitcnt lgkmcnt(0)
	v_mul_f32_e32 v5, v223, v17
	v_fmac_f32_e32 v5, v222, v16
	v_mul_f32_e32 v4, v225, v19
	v_fmac_f32_e32 v4, v224, v18
	v_add_f32_e32 v8, v9, v8
	v_add_f32_e32 v4, v5, v4
	v_add_f32_e32 v4, v8, v4
	v_add_f32_e32 v8, v12, v4
	v_lshlrev_b32_e32 v9, 16, v0
	v_and_b32_e32 v0, 0xffff0000, v0
	v_lshlrev_b32_e32 v10, 16, v1
	v_and_b32_e32 v11, 0xffff0000, v1
	v_lshlrev_b32_e32 v12, 16, v2
	v_and_b32_e32 v13, 0xffff0000, v2
	v_lshlrev_b32_e32 v14, 16, v3
	v_and_b32_e32 v15, 0xffff0000, v3
	s_waitcnt lgkmcnt(0)
	v_mul_f32_e32 v5, v227, v0
	v_fmac_f32_e32 v5, v226, v9
	v_mul_f32_e32 v4, v229, v11
	v_fmac_f32_e32 v4, v228, v10
	v_add_f32_e32 v4, v5, v4
	s_waitcnt lgkmcnt(0)
	v_mul_f32_e32 v1, v231, v13
	v_fmac_f32_e32 v1, v230, v12
	v_mul_f32_e32 v0, v233, v15
	v_fmac_f32_e32 v0, v232, v14
	v_add_f32_e32 v0, v1, v0
	v_add_f32_e32 v0, v4, v0
	v_add_f32_e32 v84, v8, v0
	global_load_dwordx4 v[32:35], v[56:57], off offset:368
	global_load_dwordx4 v[36:39], v[56:57], off offset:352
	global_load_dwordx4 v[40:43], v[56:57], off offset:336
	global_load_dwordx4 v[76:79], v[56:57], off offset:320
	global_load_dwordx4 v[16:19], v[56:57], off offset:432
	global_load_dwordx4 v[20:23], v[56:57], off offset:416
	global_load_dwordx4 v[24:27], v[56:57], off offset:400
	global_load_dwordx4 v[28:31], v[56:57], off offset:384
	global_load_dwordx4 v[0:3], v[56:57], off offset:496
	global_load_dwordx4 v[4:7], v[56:57], off offset:480
	global_load_dwordx4 v[8:11], v[56:57], off offset:464
	global_load_dwordx4 v[12:15], v[56:57], off offset:448
	ds_read_b128 v[102:105], v63 offset:512
	ds_read_b128 v[106:109], v63 offset:528
	ds_read_b128 v[110:113], v63 offset:544
	ds_read_b128 v[114:117], v63 offset:560
	ds_read_b128 v[118:121], v63 offset:576
	ds_read_b128 v[122:125], v63 offset:592
	ds_read_b128 v[126:129], v63 offset:608
	ds_read_b128 v[130:133], v63 offset:624
	ds_read_b128 v[134:137], v63 offset:640
	ds_read_b128 v[138:141], v63 offset:656
	ds_read_b128 v[142:145], v63 offset:672
	ds_read_b128 v[146:149], v63 offset:688
	ds_read_b128 v[150:153], v63 offset:704
	ds_read_b128 v[154:157], v63 offset:720
	ds_read_b128 v[158:161], v63 offset:736
	ds_read_b128 v[162:165], v63 offset:752
	ds_read_b128 v[166:169], v63 offset:768
	ds_read_b128 v[170:173], v63 offset:784
	ds_read_b128 v[174:177], v63 offset:800
	ds_read_b128 v[178:181], v63 offset:816
	ds_read_b128 v[182:185], v63 offset:832
	ds_read_b128 v[186:189], v63 offset:848
	ds_read_b128 v[190:193], v63 offset:864
	ds_read_b128 v[194:197], v63 offset:880
	ds_read_b128 v[202:205], v63 offset:896
	ds_read_b128 v[206:209], v63 offset:912
	ds_read_b128 v[210:213], v63 offset:928
	ds_read_b128 v[214:217], v63 offset:944
	ds_read_b128 v[218:221], v63 offset:960
	ds_read_b128 v[222:225], v63 offset:976
	ds_read_b128 v[226:229], v63 offset:992
	ds_read_b128 v[230:233], v63 offset:1008
	s_waitcnt lgkmcnt(0)
	s_waitcnt vmcnt(15)
	v_lshlrev_b32_e32 v56, 16, v64
	v_and_b32_e32 v57, 0xffff0000, v64
	v_lshlrev_b32_e32 v85, 16, v65
	v_and_b32_e32 v86, 0xffff0000, v65
	v_lshlrev_b32_e32 v87, 16, v66
	v_and_b32_e32 v88, 0xffff0000, v66
	v_lshlrev_b32_e32 v89, 16, v67
	v_and_b32_e32 v90, 0xffff0000, v67
	s_waitcnt lgkmcnt(1)
	v_mul_f32_e32 v57, v103, v57
	v_fmac_f32_e32 v57, v102, v56
	v_mul_f32_e32 v56, v105, v86
	v_fmac_f32_e32 v56, v104, v85
	v_add_f32_e32 v56, v57, v56
	s_waitcnt lgkmcnt(0)
	v_mul_f32_e32 v57, v107, v88
	v_fmac_f32_e32 v57, v106, v87
	v_mul_f32_e32 v64, v109, v90
	v_fmac_f32_e32 v64, v108, v89
	v_add_f32_e32 v57, v57, v64
	v_add_f32_e32 v56, v56, v57
	s_waitcnt vmcnt(14)
; #define LAS __attribute__((address_space(3)))
; __device__ __forceinline__ float dot4(f32x4 a, f32x4 b) { return (a[0] * b[0] + a[1] * b[1]) + (a[2] * b[2] + a[3] * b[3]); }
; __device__ __forceinline__ void unpack8(u32x4 w, f32x4& a, f32x4& b) { a = (f32x4){bflo(w.x), bfhi(w.x), bflo(w.y), bfhi(w.y)}; b = (f32x4){bflo(w.z), bfhi(w.z), bflo(w.w), bfhi(w.w)}; }
; __device__ __forceinline__ void sample_mix_even(Frame& F0, int j, int b) {
;     ...
;         for (int hb = 0; hb < 2; ++hb) {
;             u32x4 pr[16];
; #pragma unroll
;             for (int i = 0; i < 16; ++i) pr[i] = *(const u32x4*)(pm + hb * 128 + i * 8);
; #pragma unroll
;             for (int i = 0; i < 16; ++i) { f32x4 p0, p1; unpack8(pr[i], p0, p1); const LAS float* q = pg + hb * 128 + i * 8; a += dot4(p0, *(const LAS f32x4*)q) + dot4(p1, *(const LAS f32x4*)(q + 4)); }
;         }
	v_lshlrev_b32_e32 v57, 16, v68
	v_and_b32_e32 v68, 0xffff0000, v68
	v_add_f32_e32 v56, v84, v56
	v_lshlrev_b32_e32 v80, 16, v69
	v_and_b32_e32 v81, 0xffff0000, v69
	v_lshlrev_b32_e32 v82, 16, v70
	v_and_b32_e32 v83, 0xffff0000, v70
	v_lshlrev_b32_e32 v84, 16, v71
	v_and_b32_e32 v85, 0xffff0000, v71
	s_waitcnt lgkmcnt(0)
	v_mul_f32_e32 v65, v111, v68
	v_fmac_f32_e32 v65, v110, v57
	v_mul_f32_e32 v57, v113, v81
	v_fmac_f32_e32 v57, v112, v80
	v_add_f32_e32 v57, v65, v57
	s_waitcnt lgkmcnt(0)
	v_mul_f32_e32 v64, v115, v83
	v_mul_f32_e32 v65, v117, v85
	v_fmac_f32_e32 v64, v114, v82
	v_fmac_f32_e32 v65, v116, v84
	v_add_f32_e32 v64, v64, v65
	v_add_f32_e32 v57, v57, v64
	s_waitcnt vmcnt(13)
	v_and_b32_e32 v68, 0xffff0000, v72
	v_add_f32_e32 v56, v56, v57
	v_lshlrev_b32_e32 v57, 16, v72
	v_lshlrev_b32_e32 v72, 16, v73
	s_waitcnt lgkmcnt(0)
	v_mul_f32_e32 v65, v119, v68
	v_and_b32_e32 v73, 0xffff0000, v73
	v_fmac_f32_e32 v65, v118, v57
	v_mul_f32_e32 v57, v121, v73
	v_lshlrev_b32_e32 v80, 16, v74
	v_and_b32_e32 v74, 0xffff0000, v74
	v_lshlrev_b32_e32 v81, 16, v75
	v_and_b32_e32 v75, 0xffff0000, v75
	v_fmac_f32_e32 v57, v120, v72
	v_add_f32_e32 v57, v65, v57
	s_waitcnt lgkmcnt(0)
	v_mul_f32_e32 v64, v123, v74
	v_mul_f32_e32 v65, v125, v75
	v_fmac_f32_e32 v64, v122, v80
	v_fmac_f32_e32 v65, v124, v81
	v_add_f32_e32 v64, v64, v65
	v_add_f32_e32 v57, v57, v64
	v_add_f32_e32 v56, v56, v57
	s_waitcnt vmcnt(12)
	v_lshlrev_b32_e32 v57, 16, v44
	v_and_b32_e32 v44, 0xffff0000, v44
	v_lshlrev_b32_e32 v68, 16, v45
	v_and_b32_e32 v69, 0xffff0000, v45
	v_lshlrev_b32_e32 v70, 16, v46
	v_and_b32_e32 v71, 0xffff0000, v46
	v_lshlrev_b32_e32 v72, 16, v47
	v_and_b32_e32 v73, 0xffff0000, v47
	s_waitcnt lgkmcnt(0)
	v_mul_f32_e32 v65, v127, v44
	v_fmac_f32_e32 v65, v126, v57
	v_mul_f32_e32 v57, v129, v69
	v_fmac_f32_e32 v57, v128, v68
	v_add_f32_e32 v57, v65, v57
	s_waitcnt lgkmcnt(0)
	v_mul_f32_e32 v45, v131, v71
	v_fmac_f32_e32 v45, v130, v70
	v_mul_f32_e32 v44, v133, v73
	v_fmac_f32_e32 v44, v132, v72
	v_add_f32_e32 v44, v45, v44
	v_add_f32_e32 v44, v57, v44
	v_add_f32_e32 v56, v56, v44
	s_waitcnt vmcnt(8)
	v_and_b32_e32 v64, 0xffff0000, v76
	v_lshlrev_b32_e32 v57, 16, v76
	v_and_b32_e32 v69, 0xffff0000, v77
	v_lshlrev_b32_e32 v68, 16, v77
	s_waitcnt lgkmcnt(0)
	v_mul_f32_e32 v45, v135, v64
	v_fmac_f32_e32 v45, v134, v57
	v_mul_f32_e32 v44, v137, v69
	v_and_b32_e32 v71, 0xffff0000, v78
	v_and_b32_e32 v73, 0xffff0000, v79
	v_fmac_f32_e32 v44, v136, v68
	v_lshlrev_b32_e32 v70, 16, v78
	v_lshlrev_b32_e32 v72, 16, v79
	v_add_f32_e32 v44, v45, v44
	s_waitcnt lgkmcnt(0)
	v_mul_f32_e32 v45, v139, v71
	v_mul_f32_e32 v46, v141, v73
	v_fmac_f32_e32 v45, v138, v70
	v_fmac_f32_e32 v46, v140, v72
	v_add_f32_e32 v45, v45, v46
	v_add_f32_e32 v44, v44, v45
	v_add_f32_e32 v56, v56, v44
	v_lshlrev_b32_e32 v57, 16, v40
	v_and_b32_e32 v40, 0xffff0000, v40
	v_lshlrev_b32_e32 v64, 16, v41
	v_and_b32_e32 v65, 0xffff0000, v41
	v_lshlrev_b32_e32 v66, 16, v42
	v_and_b32_e32 v67, 0xffff0000, v42
	v_lshlrev_b32_e32 v68, 16, v43
	v_and_b32_e32 v69, 0xffff0000, v43
	s_waitcnt lgkmcnt(0)
	v_mul_f32_e32 v45, v143, v40
	v_fmac_f32_e32 v45, v142, v57
	v_mul_f32_e32 v44, v145, v65
	v_fmac_f32_e32 v44, v144, v64
	v_add_f32_e32 v44, v45, v44
	s_waitcnt lgkmcnt(0)
	v_mul_f32_e32 v41, v147, v67
	v_fmac_f32_e32 v41, v146, v66
	v_mul_f32_e32 v40, v149, v69
	v_fmac_f32_e32 v40, v148, v68
	v_add_f32_e32 v40, v41, v40
	v_add_f32_e32 v40, v44, v40
	v_add_f32_e32 v44, v56, v40
	v_lshlrev_b32_e32 v45, 16, v36
	v_and_b32_e32 v36, 0xffff0000, v36
	v_lshlrev_b32_e32 v46, 16, v37
	v_and_b32_e32 v47, 0xffff0000, v37
	v_lshlrev_b32_e32 v56, 16, v38
	v_and_b32_e32 v57, 0xffff0000, v38
	v_lshlrev_b32_e32 v64, 16, v39
	v_and_b32_e32 v65, 0xffff0000, v39
	s_waitcnt lgkmcnt(0)
	v_mul_f32_e32 v41, v151, v36
	v_fmac_f32_e32 v41, v150, v45
	v_mul_f32_e32 v40, v153, v47
	v_fmac_f32_e32 v40, v152, v46
	v_add_f32_e32 v40, v41, v40
	s_waitcnt lgkmcnt(0)
	v_mul_f32_e32 v37, v155, v57
	v_fmac_f32_e32 v37, v154, v56
	v_mul_f32_e32 v36, v157, v65
	v_fmac_f32_e32 v36, v156, v64
	v_add_f32_e32 v36, v37, v36
	v_add_f32_e32 v36, v40, v36
	v_add_f32_e32 v40, v44, v36
	v_lshlrev_b32_e32 v41, 16, v32
	v_and_b32_e32 v32, 0xffff0000, v32
	v_lshlrev_b32_e32 v42, 16, v33
	v_and_b32_e32 v43, 0xffff0000, v33
	v_lshlrev_b32_e32 v44, 16, v34
	v_and_b32_e32 v45, 0xffff0000, v34
	v_lshlrev_b32_e32 v46, 16, v35
	v_and_b32_e32 v47, 0xffff0000, v35
	s_waitcnt lgkmcnt(0)
	v_mul_f32_e32 v37, v159, v32
	v_fmac_f32_e32 v37, v158, v41
	v_mul_f32_e32 v36, v161, v43
	v_fmac_f32_e32 v36, v160, v42
	v_add_f32_e32 v36, v37, v36
	s_waitcnt lgkmcnt(0)
	v_mul_f32_e32 v33, v163, v45
	v_fmac_f32_e32 v33, v162, v44
	v_mul_f32_e32 v32, v165, v47
	v_fmac_f32_e32 v32, v164, v46
	v_add_f32_e32 v32, v33, v32
	v_add_f32_e32 v32, v36, v32
	v_add_f32_e32 v36, v40, v32
	s_waitcnt vmcnt(4)
	v_lshlrev_b32_e32 v37, 16, v28
	v_and_b32_e32 v28, 0xffff0000, v28
	v_lshlrev_b32_e32 v38, 16, v29
	v_and_b32_e32 v39, 0xffff0000, v29
	v_lshlrev_b32_e32 v40, 16, v30
	v_and_b32_e32 v41, 0xffff0000, v30
	v_lshlrev_b32_e32 v42, 16, v31
	v_and_b32_e32 v43, 0xffff0000, v31
	s_waitcnt lgkmcnt(0)
	v_mul_f32_e32 v33, v167, v28
	v_fmac_f32_e32 v33, v166, v37
	v_mul_f32_e32 v32, v169, v39
	v_fmac_f32_e32 v32, v168, v38
	v_add_f32_e32 v32, v33, v32
	s_waitcnt lgkmcnt(0)
	v_mul_f32_e32 v29, v171, v41
	v_fmac_f32_e32 v29, v170, v40
	v_mul_f32_e32 v28, v173, v43
	v_fmac_f32_e32 v28, v172, v42
	v_add_f32_e32 v28, v29, v28
	v_add_f32_e32 v28, v32, v28
	v_add_f32_e32 v32, v36, v28
	v_lshlrev_b32_e32 v33, 16, v24
	v_and_b32_e32 v24, 0xffff0000, v24
	v_lshlrev_b32_e32 v34, 16, v25
	v_and_b32_e32 v25, 0xffff0000, v25
	s_waitcnt lgkmcnt(0)
; #define LAS __attribute__((address_space(3)))
; __device__ __forceinline__ float silu_f(float x) { return x * __builtin_amdgcn_rcpf(1.f + __builtin_amdgcn_exp2f(-1.4426950408889634f * x)); }
; __device__ __forceinline__ float dot4(f32x4 a, f32x4 b) { return (a[0] * b[0] + a[1] * b[1]) + (a[2] * b[2] + a[3] * b[3]); }
; __device__ __forceinline__ void unpack8(u32x4 w, f32x4& a, f32x4& b) { a = (f32x4){bflo(w.x), bfhi(w.x), bflo(w.y), bfhi(w.y)}; b = (f32x4){bflo(w.z), bfhi(w.z), bflo(w.w), bfhi(w.w)}; }
; __device__ __forceinline__ void sample_mix_even(Frame& F0, int j, int b) {
;     ...
;         for (int hb = 0; hb < 2; ++hb) {
;             u32x4 pr[16];
; #pragma unroll
;             for (int i = 0; i < 16; ++i) pr[i] = *(const u32x4*)(pm + hb * 128 + i * 8);
; #pragma unroll
;             for (int i = 0; i < 16; ++i) { f32x4 p0, p1; unpack8(pr[i], p0, p1); const LAS float* q = pg + hb * 128 + i * 8; a += dot4(p0, *(const LAS f32x4*)q) + dot4(p1, *(const LAS f32x4*)(q + 4)); }
;         }
;         const float ya = a * FIN(12)[j * 1024 + d] * silu_f(z[1024 + d]);
;         const float vn = vv[k] * rv * FIN(15)[j * 1024 + d];
;         F.out[O_SGUV + (size_t)(j * 128 + b) * 1024 + d] = vn;
	v_mul_f32_e32 v24, v175, v24
	v_fmac_f32_e32 v24, v174, v33
	v_add_u32_e32 v28, s90, v48
	v_mul_f32_e32 v25, v177, v25
	v_ashrrev_i32_e32 v29, 31, v28
	v_fmac_f32_e32 v25, v176, v34
	v_lshlrev_b64 v[30:31], 2, v[28:29]
	v_lshl_add_u64 v[28:29], s[10:11], 0, v[30:31]
	global_load_dword v34, v[28:29], off
	v_lshlrev_b32_e32 v35, 16, v26
	v_and_b32_e32 v36, 0xffff0000, v26
	v_lshlrev_b32_e32 v37, 16, v27
	v_and_b32_e32 v38, 0xffff0000, v27
	v_add_f32_e32 v33, v24, v25
	v_lshlrev_b32_e32 v39, 16, v23
	v_and_b32_e32 v40, 0xffff0000, v23
	v_lshl_add_u64 v[30:31], s[4:5], 0, v[30:31]
	s_waitcnt lgkmcnt(0)
	v_mul_f32_e32 v25, v179, v36
	v_fmac_f32_e32 v25, v178, v35
	v_mul_f32_e32 v24, v181, v38
	v_fmac_f32_e32 v24, v180, v37
	v_add_f32_e32 v24, v25, v24
	v_add_f32_e32 v24, v33, v24
	v_add_f32_e32 v32, v32, v24
	v_lshlrev_b32_e32 v33, 16, v20
	v_and_b32_e32 v20, 0xffff0000, v20
	v_lshlrev_b32_e32 v35, 16, v21
	v_and_b32_e32 v36, 0xffff0000, v21
	v_lshlrev_b32_e32 v37, 16, v22
	v_and_b32_e32 v38, 0xffff0000, v22
	s_waitcnt lgkmcnt(0)
	v_mul_f32_e32 v25, v183, v20
	v_fmac_f32_e32 v25, v182, v33
	v_mul_f32_e32 v24, v185, v36
	v_fmac_f32_e32 v24, v184, v35
	v_add_f32_e32 v24, v25, v24
	s_waitcnt lgkmcnt(0)
	v_mul_f32_e32 v21, v187, v38
	v_fmac_f32_e32 v21, v186, v37
	v_mul_f32_e32 v20, v189, v40
	v_fmac_f32_e32 v20, v188, v39
	v_add_f32_e32 v20, v21, v20
	v_add_f32_e32 v20, v24, v20
	v_add_f32_e32 v24, v32, v20
	v_lshlrev_b32_e32 v25, 16, v16
	v_and_b32_e32 v16, 0xffff0000, v16
	v_lshlrev_b32_e32 v26, 16, v17
	v_and_b32_e32 v27, 0xffff0000, v17
	v_lshlrev_b32_e32 v32, 16, v18
	v_and_b32_e32 v33, 0xffff0000, v18
	v_lshlrev_b32_e32 v35, 16, v19
	v_and_b32_e32 v36, 0xffff0000, v19
	s_waitcnt lgkmcnt(0)
	v_mul_f32_e32 v21, v191, v16
	v_fmac_f32_e32 v21, v190, v25
	v_mul_f32_e32 v20, v193, v27
	v_fmac_f32_e32 v20, v192, v26
	v_add_f32_e32 v20, v21, v20
	s_waitcnt lgkmcnt(0)
	v_mul_f32_e32 v17, v195, v33
	v_fmac_f32_e32 v17, v194, v32
	v_mul_f32_e32 v16, v197, v36
	v_fmac_f32_e32 v16, v196, v35
	v_add_f32_e32 v16, v17, v16
	v_add_f32_e32 v16, v20, v16
	v_add_f32_e32 v20, v24, v16
	s_waitcnt vmcnt(1)
	v_lshlrev_b32_e32 v21, 16, v12
	v_and_b32_e32 v12, 0xffff0000, v12
	v_lshlrev_b32_e32 v22, 16, v13
	v_and_b32_e32 v23, 0xffff0000, v13
	v_lshlrev_b32_e32 v24, 16, v14
	v_and_b32_e32 v25, 0xffff0000, v14
	v_lshlrev_b32_e32 v26, 16, v15
	v_and_b32_e32 v27, 0xffff0000, v15
	s_waitcnt lgkmcnt(0)
	v_mul_f32_e32 v17, v203, v12
	v_fmac_f32_e32 v17, v202, v21
	v_mul_f32_e32 v16, v205, v23
	v_fmac_f32_e32 v16, v204, v22
	v_add_f32_e32 v18, v17, v16
	s_waitcnt lgkmcnt(0)
	v_mul_f32_e32 v13, v207, v25
	v_fmac_f32_e32 v13, v206, v24
	v_mul_f32_e32 v12, v209, v27
	v_fmac_f32_e32 v12, v208, v26
	v_add_f32_e32 v19, v13, v12
	v_add_co_u32_e32 v14, vcc, s70, v50
	v_mul_f32_e32 v12, v60, v59
	s_nop 0
	v_addc_co_u32_e32 v15, vcc, 0, v51, vcc
	s_waitcnt vmcnt(0)
	v_mul_f32_e32 v23, v12, v34
	v_lshl_add_u64 v[12:13], v[48:49], 2, s[2:3]
	s_mov_b32 s2, 0x54b0000
	v_add_co_u32_e32 v16, vcc, s2, v12
	global_load_dword v21, v[30:31], off
	s_nop 0
	v_addc_co_u32_e32 v17, vcc, 0, v13, vcc
	global_load_dword v22, v[14:15], off offset:-4096
	v_add_f32_e32 v18, v18, v19
	global_store_dword v[16:17], v23, off
	v_add_co_u32_e32 v16, vcc, s94, v50
	v_add_f32_e32 v18, v20, v18
	s_nop 0
	v_addc_co_u32_e32 v17, vcc, 0, v51, vcc
	global_load_dword v24, v[16:17], off
	v_lshlrev_b64 v[16:17], 16, v[54:55]
	v_lshl_add_u64 v[16:17], s[6:7], 0, v[16:17]
	global_load_dword v19, v[16:17], off
	v_lshlrev_b32_e32 v16, 7, v54
	v_ashrrev_i32_e32 v17, 31, v16
	v_lshl_add_u64 v[16:17], v[16:17], 2, s[8:9]
	global_load_dword v25, v[16:17], off
	global_load_dword v26, v[14:15], off
	v_lshlrev_b32_e32 v20, 16, v8
	v_and_b32_e32 v8, 0xffff0000, v8
	v_lshlrev_b32_e32 v27, 16, v9
	v_and_b32_e32 v32, 0xffff0000, v9
	v_lshlrev_b32_e32 v33, 16, v10
	v_and_b32_e32 v34, 0xffff0000, v10
	v_lshlrev_b32_e32 v35, 16, v11
	v_and_b32_e32 v36, 0xffff0000, v11
	s_waitcnt lgkmcnt(0)
	v_mul_f32_e32 v15, v211, v8
	v_fmac_f32_e32 v15, v210, v20
	v_mul_f32_e32 v14, v213, v32
	v_fmac_f32_e32 v14, v212, v27
	v_add_f32_e32 v14, v15, v14
	s_waitcnt lgkmcnt(0)
	v_mul_f32_e32 v9, v215, v34
	v_fmac_f32_e32 v9, v214, v33
	v_mul_f32_e32 v8, v217, v36
	v_fmac_f32_e32 v8, v216, v35
	v_add_f32_e32 v8, v9, v8
	v_add_f32_e32 v8, v14, v8
	v_add_f32_e32 v14, v18, v8
	v_lshlrev_b32_e32 v15, 16, v4
	v_and_b32_e32 v4, 0xffff0000, v4
	v_lshlrev_b32_e32 v16, 16, v5
	v_and_b32_e32 v17, 0xffff0000, v5
	v_lshlrev_b32_e32 v18, 16, v6
	v_and_b32_e32 v20, 0xffff0000, v6
	v_lshlrev_b32_e32 v27, 16, v7
	v_and_b32_e32 v32, 0xffff0000, v7
	s_waitcnt lgkmcnt(0)
	v_mul_f32_e32 v9, v219, v4
	v_fmac_f32_e32 v9, v218, v15
	v_mul_f32_e32 v8, v221, v17
	v_fmac_f32_e32 v8, v220, v16
	v_add_f32_e32 v8, v9, v8
	s_waitcnt lgkmcnt(0)
	v_mul_f32_e32 v5, v223, v20
	v_fmac_f32_e32 v5, v222, v18
	v_mul_f32_e32 v4, v225, v32
	v_fmac_f32_e32 v4, v224, v27
	v_add_f32_e32 v4, v5, v4
	v_add_f32_e32 v4, v8, v4
	v_add_f32_e32 v8, v14, v4
	v_lshlrev_b32_e32 v9, 16, v0
	v_and_b32_e32 v0, 0xffff0000, v0
	v_lshlrev_b32_e32 v10, 16, v1
	v_and_b32_e32 v11, 0xffff0000, v1
	v_lshlrev_b32_e32 v14, 16, v2
	v_and_b32_e32 v15, 0xffff0000, v2
	v_lshlrev_b32_e32 v16, 16, v3
	v_and_b32_e32 v17, 0xffff0000, v3
	s_waitcnt lgkmcnt(0)
	v_mul_f32_e32 v5, v227, v0
	v_fmac_f32_e32 v5, v226, v9
	v_mul_f32_e32 v4, v229, v11
	v_fmac_f32_e32 v4, v228, v10
	v_add_f32_e32 v4, v5, v4
	s_waitcnt lgkmcnt(0)
	v_mul_f32_e32 v1, v231, v15
	v_fmac_f32_e32 v1, v230, v14
	v_mul_f32_e32 v0, v233, v17
	v_fmac_f32_e32 v0, v232, v16
	v_add_f32_e32 v0, v1, v0
	s_waitcnt vmcnt(5)
; __device__ __forceinline__ unsigned cvt_pk_bf16(float lo, float hi) { const f32x2cv v = {lo, hi}; return __builtin_bit_cast(unsigned, __builtin_convertvector(v, bf16x2cv)); }
; #define LAS __attribute__((address_space(3)))
; __device__ __forceinline__ float silu_f(float x) { return x * __builtin_amdgcn_rcpf(1.f + __builtin_amdgcn_exp2f(-1.4426950408889634f * x)); }
; __device__ __forceinline__ float dot4(f32x4 a, f32x4 b) { return (a[0] * b[0] + a[1] * b[1]) + (a[2] * b[2] + a[3] * b[3]); }
; __device__ __forceinline__ void unpack8(u32x4 w, f32x4& a, f32x4& b) { a = (f32x4){bflo(w.x), bfhi(w.x), bflo(w.y), bfhi(w.y)}; b = (f32x4){bflo(w.z), bfhi(w.z), bflo(w.w), bfhi(w.w)}; }
; __device__ __forceinline__ void sample_mix_even(Frame& F0, int j, int b) {
;     ...
;         const int d = tid + 512 * k, g = d >> 8, dd = d & 255;
;         const bf16_t* pm = ((bf16_t*)(F.ws + WS_PMT)) + (size_t)(j * 4 + g) * 65536 + (size_t)dd * 256; const LAS float* pg = pl + g * 256;
;         float a = 0.f;
; #pragma unroll
;         for (int hb = 0; hb < 2; ++hb) {
;             u32x4 pr[16];
; #pragma unroll
;             for (int i = 0; i < 16; ++i) pr[i] = *(const u32x4*)(pm + hb * 128 + i * 8);
; #pragma unroll
;             for (int i = 0; i < 16; ++i) { f32x4 p0, p1; unpack8(pr[i], p0, p1); const LAS float* q = pg + hb * 128 + i * 8; a += dot4(p0, *(const LAS f32x4*)q) + dot4(p1, *(const LAS f32x4*)(q + 4)); }
;     ...
;         const float ya = a * FIN(12)[j * 1024 + d] * silu_f(z[1024 + d]);
;         const float vn = vv[k] * rv * FIN(15)[j * 1024 + d];
;         F.out[O_SGUV + (size_t)(j * 128 + b) * 1024 + d] = vn;
;         const float mixed = FIN(13)[(size_t)(j * 4 + g) * 16384] * vn + FIN(14)[(j * 4 + g) * 128];
;         const float yb = z[2048 + d] * mixed * silu_f(z[4096 + d]);
;         ((bf16_t*)(F.ws + WS_SA2))[(size_t)b * 2048 + d] = (bf16_t)(cvt_pk_bf16(ya, 0.f) & 0xffffu); ((bf16_t*)(F.ws + WS_SA2))[(size_t)b * 2048 + 1024 + d] = (bf16_t)(cvt_pk_bf16(yb, 0.f) & 0xffffu);
	v_mul_f32_e32 v3, 0xbfb8aa3b, v22
	v_exp_f32_e32 v3, v3
	v_add_f32_e32 v0, v4, v0
	v_add_f32_e32 v0, v8, v0
	v_mul_f32_e32 v0, v21, v0
	v_add_f32_e32 v1, 1.0, v3
	v_rcp_f32_e32 v1, v1
	s_waitcnt vmcnt(3)
	v_mul_f32_e32 v2, 0xbfb8aa3b, v24
	v_exp_f32_e32 v2, v2
	v_mul_f32_e32 v1, v22, v1
	v_mul_f32_e32 v0, v0, v1
	v_cvt_pk_bf16_f32 v3, v0, s0
	v_add_f32_e32 v2, 1.0, v2
	v_rcp_f32_e32 v2, v2
	s_waitcnt vmcnt(1)
	v_fmac_f32_e32 v25, v23, v19
	s_waitcnt vmcnt(0)
	v_mul_f32_e32 v1, v26, v25
	v_add_u32_e32 v22, s24, v62
	v_mul_f32_e32 v2, v24, v2
	v_mul_f32_e32 v2, v1, v2
	v_lshl_add_u64 v[0:1], v[48:49], 1, s[0:1]
	s_mov_b64 s[0:1], 0x1b500000
	v_lshl_add_u64 v[20:21], v[0:1], 0, s[0:1]
	s_mov_b32 s0, 0x1b500000
	v_add_co_u32_e32 v0, vcc, s0, v0
	v_ashrrev_i32_e32 v23, 31, v22
	s_nop 0
	v_addc_co_u32_e32 v1, vcc, 0, v1, vcc
	global_store_short v[0:1], v3, off
	v_cvt_pk_bf16_f32 v0, v2, s0
	global_store_short v[20:21], v0, off offset:2048
	v_lshlrev_b64 v[0:1], 17, v[22:23]
	v_lshl_add_u64 v[32:33], v[52:53], 0, v[0:1]
	global_load_dwordx4 v[36:39], v[32:33], off
	global_load_dwordx4 v[40:43], v[32:33], off offset:16
	global_load_dwordx4 v[44:47], v[32:33], off offset:32
	s_mov_b64 s[0:1], 0x800
	v_lshl_add_u64 v[24:25], v[50:51], 0, s[0:1]
	global_load_dwordx4 v[48:51], v[32:33], off offset:48
	s_mov_b64 s[0:1], 0x54b0000
	v_and_b32_e32 v0, 0x3fffff00, v61
	v_lshl_add_u64 v[26:27], v[12:13], 0, s[0:1]
	v_lshl_add_u32 v34, v0, 2, 0
	global_load_dwordx4 v[52:55], v[32:33], off offset:112
	global_load_dwordx4 v[60:63], v[32:33], off offset:96
	global_load_dwordx4 v[64:67], v[32:33], off offset:80
	global_load_dwordx4 v[68:71], v[32:33], off offset:64
	global_load_dwordx4 v[16:19], v[32:33], off offset:176
	global_load_dwordx4 v[72:75], v[32:33], off offset:160
	global_load_dwordx4 v[76:79], v[32:33], off offset:144
	global_load_dwordx4 v[80:83], v[32:33], off offset:128
	global_load_dwordx4 v[0:3], v[32:33], off offset:240
	global_load_dwordx4 v[4:7], v[32:33], off offset:224
	global_load_dwordx4 v[8:11], v[32:33], off offset:208
	global_load_dwordx4 v[12:15], v[32:33], off offset:192
	ds_read_b128 v[102:105], v34
	ds_read_b128 v[106:109], v34 offset:16
	ds_read_b128 v[110:113], v34 offset:32
	ds_read_b128 v[114:117], v34 offset:48
	ds_read_b128 v[118:121], v34 offset:64
	ds_read_b128 v[122:125], v34 offset:80
	ds_read_b128 v[126:129], v34 offset:96
	ds_read_b128 v[130:133], v34 offset:112
	ds_read_b128 v[134:137], v34 offset:128
	ds_read_b128 v[138:141], v34 offset:144
	ds_read_b128 v[142:145], v34 offset:160
	ds_read_b128 v[146:149], v34 offset:176
	ds_read_b128 v[150:153], v34 offset:192
	ds_read_b128 v[154:157], v34 offset:208
	ds_read_b128 v[158:161], v34 offset:224
	ds_read_b128 v[162:165], v34 offset:240
	ds_read_b128 v[166:169], v34 offset:256
	ds_read_b128 v[170:173], v34 offset:272
	ds_read_b128 v[174:177], v34 offset:288
	ds_read_b128 v[178:181], v34 offset:304
	ds_read_b128 v[182:185], v34 offset:320
	ds_read_b128 v[186:189], v34 offset:336
	ds_read_b128 v[190:193], v34 offset:352
	ds_read_b128 v[194:197], v34 offset:368
	ds_read_b128 v[202:205], v34 offset:384
	ds_read_b128 v[206:209], v34 offset:400
	ds_read_b128 v[210:213], v34 offset:416
	ds_read_b128 v[214:217], v34 offset:432
	ds_read_b128 v[218:221], v34 offset:448
	ds_read_b128 v[222:225], v34 offset:464
	ds_read_b128 v[226:229], v34 offset:480
	ds_read_b128 v[230:233], v34 offset:496
	s_waitcnt lgkmcnt(0)
	s_waitcnt vmcnt(15)
	v_lshlrev_b32_e32 v35, 16, v36
	v_and_b32_e32 v56, 0xffff0000, v36
	v_lshlrev_b32_e32 v57, 16, v37
	v_and_b32_e32 v96, 0xffff0000, v37
	v_lshlrev_b32_e32 v97, 16, v38
	v_and_b32_e32 v98, 0xffff0000, v38
	v_lshlrev_b32_e32 v99, 16, v39
	v_and_b32_e32 v100, 0xffff0000, v39
	s_waitcnt lgkmcnt(3)
	v_mul_f32_e32 v56, v103, v56
	v_fmac_f32_e32 v56, v102, v35
	s_waitcnt lgkmcnt(2)
	v_mul_f32_e32 v37, v107, v98
	v_mul_f32_e32 v35, v105, v96
	v_fmac_f32_e32 v37, v106, v97
	v_mul_f32_e32 v36, v109, v100
	v_fmac_f32_e32 v35, v104, v57
	v_fmac_f32_e32 v36, v108, v99
	v_add_f32_e32 v35, v56, v35
	v_add_f32_e32 v36, v37, v36
	s_waitcnt vmcnt(14)
	v_and_b32_e32 v37, 0xffff0000, v40
	v_add_f32_e32 v35, v35, v36
	v_lshlrev_b32_e32 v36, 16, v40
	v_and_b32_e32 v39, 0xffff0000, v41
	s_waitcnt lgkmcnt(1)
	v_mul_f32_e32 v37, v111, v37
	v_lshlrev_b32_e32 v38, 16, v41
	v_fmac_f32_e32 v37, v110, v36
	v_mul_f32_e32 v36, v113, v39
	v_lshlrev_b32_e32 v40, 16, v42
	v_and_b32_e32 v41, 0xffff0000, v42
	v_lshlrev_b32_e32 v42, 16, v43
	v_and_b32_e32 v43, 0xffff0000, v43
	v_fmac_f32_e32 v36, v112, v38
	v_add_f32_e32 v36, v37, v36
	s_waitcnt lgkmcnt(0)
	v_mul_f32_e32 v37, v115, v41
	v_mul_f32_e32 v38, v117, v43
	v_fmac_f32_e32 v37, v114, v40
	v_fmac_f32_e32 v38, v116, v42
	v_add_f32_e32 v37, v37, v38
	v_add_f32_e32 v35, 0, v35
	v_add_f32_e32 v36, v36, v37
	v_add_f32_e32 v35, v35, v36
	s_waitcnt vmcnt(13)
	v_and_b32_e32 v40, 0xffff0000, v44
	v_lshlrev_b32_e32 v56, 16, v44
	v_lshlrev_b32_e32 v44, 16, v45
	v_and_b32_e32 v45, 0xffff0000, v45
	s_waitcnt lgkmcnt(0)
	v_mul_f32_e32 v37, v119, v40
	v_fmac_f32_e32 v37, v118, v56
	v_mul_f32_e32 v36, v121, v45
	v_lshlrev_b32_e32 v57, 16, v46
	v_and_b32_e32 v46, 0xffff0000, v46
	v_lshlrev_b32_e32 v84, 16, v47
	v_and_b32_e32 v47, 0xffff0000, v47
	v_fmac_f32_e32 v36, v120, v44
	v_add_f32_e32 v36, v37, v36
	s_waitcnt lgkmcnt(0)
	v_mul_f32_e32 v37, v123, v46
	v_mul_f32_e32 v38, v125, v47
	v_fmac_f32_e32 v37, v122, v57
	v_fmac_f32_e32 v38, v124, v84
	v_add_f32_e32 v37, v37, v38
	v_add_f32_e32 v36, v36, v37
	v_add_f32_e32 v35, v35, v36
	s_waitcnt vmcnt(12)
	v_and_b32_e32 v40, 0xffff0000, v48
	v_lshlrev_b32_e32 v44, 16, v48
	v_and_b32_e32 v46, 0xffff0000, v49
	v_lshlrev_b32_e32 v45, 16, v49
	s_waitcnt lgkmcnt(0)
; #define LAS __attribute__((address_space(3)))
; __device__ __forceinline__ float dot4(f32x4 a, f32x4 b) { return (a[0] * b[0] + a[1] * b[1]) + (a[2] * b[2] + a[3] * b[3]); }
; __device__ __forceinline__ void unpack8(u32x4 w, f32x4& a, f32x4& b) { a = (f32x4){bflo(w.x), bfhi(w.x), bflo(w.y), bfhi(w.y)}; b = (f32x4){bflo(w.z), bfhi(w.z), bflo(w.w), bfhi(w.w)}; }
; __device__ __forceinline__ void sample_mix_even(Frame& F0, int j, int b) {
;     ...
;         for (int hb = 0; hb < 2; ++hb) {
;             u32x4 pr[16];
; #pragma unroll
;             for (int i = 0; i < 16; ++i) pr[i] = *(const u32x4*)(pm + hb * 128 + i * 8);
; #pragma unroll
;             for (int i = 0; i < 16; ++i) { f32x4 p0, p1; unpack8(pr[i], p0, p1); const LAS float* q = pg + hb * 128 + i * 8; a += dot4(p0, *(const LAS f32x4*)q) + dot4(p1, *(const LAS f32x4*)(q + 4)); }
;         }
	v_mul_f32_e32 v37, v127, v40
	v_fmac_f32_e32 v37, v126, v44
	v_mul_f32_e32 v36, v129, v46
	v_lshlrev_b32_e32 v47, 16, v50
	v_and_b32_e32 v48, 0xffff0000, v50
	v_and_b32_e32 v50, 0xffff0000, v51
	v_fmac_f32_e32 v36, v128, v45
	v_lshlrev_b32_e32 v49, 16, v51
	v_add_f32_e32 v36, v37, v36
	s_waitcnt lgkmcnt(0)
	v_mul_f32_e32 v37, v131, v48
	v_mul_f32_e32 v38, v133, v50
	v_fmac_f32_e32 v37, v130, v47
	v_fmac_f32_e32 v38, v132, v49
	v_add_f32_e32 v37, v37, v38
	v_add_f32_e32 v36, v36, v37
	v_add_f32_e32 v35, v35, v36
	s_waitcnt vmcnt(8)
	v_and_b32_e32 v40, 0xffff0000, v68
	v_lshlrev_b32_e32 v44, 16, v68
	v_and_b32_e32 v46, 0xffff0000, v69
	v_lshlrev_b32_e32 v45, 16, v69
	s_waitcnt lgkmcnt(0)
	v_mul_f32_e32 v37, v135, v40
	v_fmac_f32_e32 v37, v134, v44
	v_mul_f32_e32 v36, v137, v46
	v_and_b32_e32 v48, 0xffff0000, v70
	v_and_b32_e32 v50, 0xffff0000, v71
	v_fmac_f32_e32 v36, v136, v45
	v_lshlrev_b32_e32 v47, 16, v70
	v_lshlrev_b32_e32 v49, 16, v71
	v_add_f32_e32 v36, v37, v36
	s_waitcnt lgkmcnt(0)
	v_mul_f32_e32 v37, v139, v48
	v_mul_f32_e32 v38, v141, v50
	v_fmac_f32_e32 v37, v138, v47
	v_fmac_f32_e32 v38, v140, v49
	v_add_f32_e32 v37, v37, v38
	v_add_f32_e32 v36, v36, v37
	v_add_f32_e32 v35, v35, v36
	v_and_b32_e32 v40, 0xffff0000, v64
	v_lshlrev_b32_e32 v44, 16, v64
	v_and_b32_e32 v46, 0xffff0000, v65
	v_lshlrev_b32_e32 v45, 16, v65
	s_waitcnt lgkmcnt(0)
	v_mul_f32_e32 v37, v143, v40
	v_fmac_f32_e32 v37, v142, v44
	v_mul_f32_e32 v36, v145, v46
	v_and_b32_e32 v48, 0xffff0000, v66
	v_and_b32_e32 v50, 0xffff0000, v67
	v_fmac_f32_e32 v36, v144, v45
	v_lshlrev_b32_e32 v47, 16, v66
	v_lshlrev_b32_e32 v49, 16, v67
	v_add_f32_e32 v36, v37, v36
	s_waitcnt lgkmcnt(0)
	v_mul_f32_e32 v37, v147, v48
	v_mul_f32_e32 v38, v149, v50
	v_fmac_f32_e32 v37, v146, v47
	v_fmac_f32_e32 v38, v148, v49
	v_add_f32_e32 v37, v37, v38
	v_add_f32_e32 v36, v36, v37
	v_add_f32_e32 v35, v35, v36
	v_and_b32_e32 v40, 0xffff0000, v60
	v_lshlrev_b32_e32 v44, 16, v60
	v_and_b32_e32 v46, 0xffff0000, v61
	v_lshlrev_b32_e32 v45, 16, v61
	s_waitcnt lgkmcnt(0)
	v_mul_f32_e32 v37, v151, v40
	v_fmac_f32_e32 v37, v150, v44
	v_mul_f32_e32 v36, v153, v46
	v_and_b32_e32 v48, 0xffff0000, v62
	v_and_b32_e32 v50, 0xffff0000, v63
	v_fmac_f32_e32 v36, v152, v45
	v_lshlrev_b32_e32 v47, 16, v62
	v_lshlrev_b32_e32 v49, 16, v63
	v_add_f32_e32 v36, v37, v36
	s_waitcnt lgkmcnt(0)
	v_mul_f32_e32 v37, v155, v48
	v_mul_f32_e32 v38, v157, v50
	v_fmac_f32_e32 v37, v154, v47
	v_fmac_f32_e32 v38, v156, v49
	v_add_f32_e32 v37, v37, v38
	v_add_f32_e32 v36, v36, v37
	v_add_f32_e32 v35, v35, v36
	v_and_b32_e32 v40, 0xffff0000, v52
	v_lshlrev_b32_e32 v44, 16, v52
	v_and_b32_e32 v46, 0xffff0000, v53
	v_lshlrev_b32_e32 v45, 16, v53
	s_waitcnt lgkmcnt(0)
	v_mul_f32_e32 v37, v159, v40
	v_fmac_f32_e32 v37, v158, v44
	v_mul_f32_e32 v36, v161, v46
	v_and_b32_e32 v48, 0xffff0000, v54
	v_and_b32_e32 v50, 0xffff0000, v55
	v_fmac_f32_e32 v36, v160, v45
	v_lshlrev_b32_e32 v47, 16, v54
	v_lshlrev_b32_e32 v49, 16, v55
	v_add_f32_e32 v36, v37, v36
	s_waitcnt lgkmcnt(0)
	v_mul_f32_e32 v37, v163, v48
	v_mul_f32_e32 v38, v165, v50
	v_fmac_f32_e32 v37, v162, v47
	v_fmac_f32_e32 v38, v164, v49
	v_add_f32_e32 v37, v37, v38
	v_add_f32_e32 v36, v36, v37
	v_add_f32_e32 v35, v35, v36
	s_waitcnt vmcnt(4)
	v_and_b32_e32 v40, 0xffff0000, v80
	v_lshlrev_b32_e32 v44, 16, v80
	v_and_b32_e32 v46, 0xffff0000, v81
	v_lshlrev_b32_e32 v45, 16, v81
	s_waitcnt lgkmcnt(0)
	v_mul_f32_e32 v37, v167, v40
	v_fmac_f32_e32 v37, v166, v44
	v_mul_f32_e32 v36, v169, v46
	v_and_b32_e32 v48, 0xffff0000, v82
	v_and_b32_e32 v50, 0xffff0000, v83
	v_fmac_f32_e32 v36, v168, v45
	v_lshlrev_b32_e32 v47, 16, v82
	v_lshlrev_b32_e32 v49, 16, v83
	v_add_f32_e32 v36, v37, v36
	s_waitcnt lgkmcnt(0)
	v_mul_f32_e32 v37, v171, v48
	v_mul_f32_e32 v38, v173, v50
	v_fmac_f32_e32 v37, v170, v47
	v_fmac_f32_e32 v38, v172, v49
	v_add_f32_e32 v37, v37, v38
	v_add_f32_e32 v36, v36, v37
	v_add_f32_e32 v35, v35, v36
	v_and_b32_e32 v40, 0xffff0000, v76
	v_lshlrev_b32_e32 v44, 16, v76
	v_and_b32_e32 v46, 0xffff0000, v77
	v_lshlrev_b32_e32 v45, 16, v77
	s_waitcnt lgkmcnt(0)
	v_mul_f32_e32 v37, v175, v40
	v_fmac_f32_e32 v37, v174, v44
	v_mul_f32_e32 v36, v177, v46
	v_and_b32_e32 v48, 0xffff0000, v78
	v_and_b32_e32 v50, 0xffff0000, v79
	v_fmac_f32_e32 v36, v176, v45
	v_lshlrev_b32_e32 v47, 16, v78
	v_lshlrev_b32_e32 v49, 16, v79
	v_add_f32_e32 v36, v37, v36
	s_waitcnt lgkmcnt(0)
	v_mul_f32_e32 v37, v179, v48
	v_mul_f32_e32 v38, v181, v50
	v_fmac_f32_e32 v37, v178, v47
	v_fmac_f32_e32 v38, v180, v49
	v_add_f32_e32 v37, v37, v38
	v_add_f32_e32 v36, v36, v37
	v_add_f32_e32 v35, v35, v36
	v_and_b32_e32 v40, 0xffff0000, v72
	v_lshlrev_b32_e32 v44, 16, v72
	v_and_b32_e32 v46, 0xffff0000, v73
	v_lshlrev_b32_e32 v45, 16, v73
	s_waitcnt lgkmcnt(0)
	v_mul_f32_e32 v37, v183, v40
	v_fmac_f32_e32 v37, v182, v44
	v_mul_f32_e32 v36, v185, v46
	v_and_b32_e32 v48, 0xffff0000, v74
	v_and_b32_e32 v50, 0xffff0000, v75
	v_fmac_f32_e32 v36, v184, v45
	v_lshlrev_b32_e32 v47, 16, v74
	v_lshlrev_b32_e32 v49, 16, v75
	v_add_f32_e32 v36, v37, v36
	s_waitcnt lgkmcnt(0)
	v_mul_f32_e32 v37, v187, v48
	v_mul_f32_e32 v38, v189, v50
	v_fmac_f32_e32 v37, v186, v47
	v_fmac_f32_e32 v38, v188, v49
	v_add_f32_e32 v37, v37, v38
	v_add_f32_e32 v36, v36, v37
	v_add_f32_e32 v35, v35, v36
	v_lshlrev_b32_e32 v40, 16, v16
	v_and_b32_e32 v16, 0xffff0000, v16
	v_lshlrev_b32_e32 v41, 16, v17
	v_and_b32_e32 v42, 0xffff0000, v17
	v_lshlrev_b32_e32 v43, 16, v18
	v_and_b32_e32 v44, 0xffff0000, v18
	v_lshlrev_b32_e32 v45, 16, v19
	v_and_b32_e32 v46, 0xffff0000, v19
	s_waitcnt lgkmcnt(0)
; #define LAS __attribute__((address_space(3)))
; __device__ __forceinline__ float dot4(f32x4 a, f32x4 b) { return (a[0] * b[0] + a[1] * b[1]) + (a[2] * b[2] + a[3] * b[3]); }
; __device__ __forceinline__ void unpack8(u32x4 w, f32x4& a, f32x4& b) { a = (f32x4){bflo(w.x), bfhi(w.x), bflo(w.y), bfhi(w.y)}; b = (f32x4){bflo(w.z), bfhi(w.z), bflo(w.w), bfhi(w.w)}; }
; __device__ __forceinline__ void sample_mix_even(Frame& F0, int j, int b) {
;     ...
;         for (int hb = 0; hb < 2; ++hb) {
;             u32x4 pr[16];
; #pragma unroll
;             for (int i = 0; i < 16; ++i) pr[i] = *(const u32x4*)(pm + hb * 128 + i * 8);
; #pragma unroll
;             for (int i = 0; i < 16; ++i) { f32x4 p0, p1; unpack8(pr[i], p0, p1); const LAS float* q = pg + hb * 128 + i * 8; a += dot4(p0, *(const LAS f32x4*)q) + dot4(p1, *(const LAS f32x4*)(q + 4)); }
;         }
	v_mul_f32_e32 v37, v191, v16
	v_fmac_f32_e32 v37, v190, v40
	v_mul_f32_e32 v36, v193, v42
	v_fmac_f32_e32 v36, v192, v41
	v_add_f32_e32 v36, v37, v36
	s_waitcnt lgkmcnt(0)
	v_mul_f32_e32 v17, v195, v44
	v_fmac_f32_e32 v17, v194, v43
	v_mul_f32_e32 v16, v197, v46
	v_fmac_f32_e32 v16, v196, v45
	v_add_f32_e32 v16, v17, v16
	v_add_f32_e32 v16, v36, v16
	v_add_f32_e32 v35, v35, v16
	s_waitcnt vmcnt(0)
	v_lshlrev_b32_e32 v36, 16, v12
	v_and_b32_e32 v12, 0xffff0000, v12
	v_lshlrev_b32_e32 v37, 16, v13
	v_and_b32_e32 v38, 0xffff0000, v13
	v_lshlrev_b32_e32 v39, 16, v14
	v_and_b32_e32 v40, 0xffff0000, v14
	v_lshlrev_b32_e32 v41, 16, v15
	v_and_b32_e32 v42, 0xffff0000, v15
	s_waitcnt lgkmcnt(0)
	v_mul_f32_e32 v17, v203, v12
	v_fmac_f32_e32 v17, v202, v36
	v_mul_f32_e32 v16, v205, v38
	v_fmac_f32_e32 v16, v204, v37
	v_add_f32_e32 v16, v17, v16
	s_waitcnt lgkmcnt(0)
	v_mul_f32_e32 v13, v207, v40
	v_fmac_f32_e32 v13, v206, v39
	v_mul_f32_e32 v12, v209, v42
	v_fmac_f32_e32 v12, v208, v41
	v_add_f32_e32 v12, v13, v12
	v_add_f32_e32 v12, v16, v12
	v_add_f32_e32 v16, v35, v12
	global_load_dwordx4 v[36:39], v[32:33], off offset:256
	v_lshlrev_b32_e32 v17, 16, v8
	v_and_b32_e32 v8, 0xffff0000, v8
	v_lshlrev_b32_e32 v18, 16, v9
	v_and_b32_e32 v19, 0xffff0000, v9
	v_lshlrev_b32_e32 v35, 16, v10
	v_and_b32_e32 v40, 0xffff0000, v10
	v_lshlrev_b32_e32 v41, 16, v11
	v_and_b32_e32 v42, 0xffff0000, v11
	s_waitcnt lgkmcnt(0)
	v_mul_f32_e32 v13, v211, v8
	v_fmac_f32_e32 v13, v210, v17
	v_mul_f32_e32 v12, v213, v19
	v_fmac_f32_e32 v12, v212, v18
	v_add_f32_e32 v12, v13, v12
	s_waitcnt lgkmcnt(0)
	v_mul_f32_e32 v9, v215, v40
	v_fmac_f32_e32 v9, v214, v35
	v_mul_f32_e32 v8, v217, v42
	v_fmac_f32_e32 v8, v216, v41
	global_load_dwordx4 v[40:43], v[32:33], off offset:272
	v_add_f32_e32 v8, v9, v8
	v_add_f32_e32 v8, v12, v8
	v_add_f32_e32 v12, v16, v8
	global_load_dwordx4 v[44:47], v[32:33], off offset:288
	v_lshlrev_b32_e32 v13, 16, v4
	v_and_b32_e32 v4, 0xffff0000, v4
	v_lshlrev_b32_e32 v14, 16, v5
	v_and_b32_e32 v15, 0xffff0000, v5
	v_lshlrev_b32_e32 v16, 16, v6
	v_and_b32_e32 v17, 0xffff0000, v6
	v_lshlrev_b32_e32 v18, 16, v7
	v_and_b32_e32 v19, 0xffff0000, v7
	s_waitcnt lgkmcnt(0)
	v_mul_f32_e32 v9, v219, v4
	v_fmac_f32_e32 v9, v218, v13
	v_mul_f32_e32 v8, v221, v15
	v_fmac_f32_e32 v8, v220, v14
	global_load_dwordx4 v[48:51], v[32:33], off offset:304
	s_waitcnt lgkmcnt(0)
	v_mul_f32_e32 v5, v223, v17
	v_fmac_f32_e32 v5, v222, v16
	v_mul_f32_e32 v4, v225, v19
	v_fmac_f32_e32 v4, v224, v18
	v_add_f32_e32 v8, v9, v8
	v_add_f32_e32 v4, v5, v4
	v_add_f32_e32 v4, v8, v4
	v_add_f32_e32 v8, v12, v4
	v_lshlrev_b32_e32 v9, 16, v0
	v_and_b32_e32 v0, 0xffff0000, v0
	v_lshlrev_b32_e32 v10, 16, v1
	v_and_b32_e32 v11, 0xffff0000, v1
	v_lshlrev_b32_e32 v12, 16, v2
	v_and_b32_e32 v13, 0xffff0000, v2
	v_lshlrev_b32_e32 v14, 16, v3
	v_and_b32_e32 v15, 0xffff0000, v3
	s_waitcnt lgkmcnt(0)
	v_mul_f32_e32 v5, v227, v0
	v_fmac_f32_e32 v5, v226, v9
	v_mul_f32_e32 v4, v229, v11
	v_fmac_f32_e32 v4, v228, v10
	v_add_f32_e32 v4, v5, v4
	s_waitcnt lgkmcnt(0)
	v_mul_f32_e32 v1, v231, v13
	v_fmac_f32_e32 v1, v230, v12
	v_mul_f32_e32 v0, v233, v15
	v_fmac_f32_e32 v0, v232, v14
	v_add_f32_e32 v0, v1, v0
	v_add_f32_e32 v0, v4, v0
	v_add_f32_e32 v35, v8, v0
	global_load_dwordx4 v[52:55], v[32:33], off offset:368
	global_load_dwordx4 v[60:63], v[32:33], off offset:352
	global_load_dwordx4 v[64:67], v[32:33], off offset:336
	global_load_dwordx4 v[68:71], v[32:33], off offset:320
	global_load_dwordx4 v[16:19], v[32:33], off offset:432
	global_load_dwordx4 v[72:75], v[32:33], off offset:416
	global_load_dwordx4 v[76:79], v[32:33], off offset:400
	global_load_dwordx4 v[80:83], v[32:33], off offset:384
	global_load_dwordx4 v[0:3], v[32:33], off offset:496
	global_load_dwordx4 v[4:7], v[32:33], off offset:480
	global_load_dwordx4 v[8:11], v[32:33], off offset:464
	global_load_dwordx4 v[12:15], v[32:33], off offset:448
	ds_read_b128 v[102:105], v34 offset:512
	ds_read_b128 v[106:109], v34 offset:528
	ds_read_b128 v[110:113], v34 offset:544
	ds_read_b128 v[114:117], v34 offset:560
	ds_read_b128 v[118:121], v34 offset:576
	ds_read_b128 v[122:125], v34 offset:592
	ds_read_b128 v[126:129], v34 offset:608
	ds_read_b128 v[130:133], v34 offset:624
	ds_read_b128 v[134:137], v34 offset:640
	ds_read_b128 v[138:141], v34 offset:656
	ds_read_b128 v[142:145], v34 offset:672
	ds_read_b128 v[146:149], v34 offset:688
	ds_read_b128 v[150:153], v34 offset:704
	ds_read_b128 v[154:157], v34 offset:720
	ds_read_b128 v[158:161], v34 offset:736
	ds_read_b128 v[162:165], v34 offset:752
	ds_read_b128 v[166:169], v34 offset:768
	ds_read_b128 v[170:173], v34 offset:784
	ds_read_b128 v[174:177], v34 offset:800
	ds_read_b128 v[178:181], v34 offset:816
	ds_read_b128 v[182:185], v34 offset:832
	ds_read_b128 v[186:189], v34 offset:848
	ds_read_b128 v[190:193], v34 offset:864
	ds_read_b128 v[194:197], v34 offset:880
	ds_read_b128 v[202:205], v34 offset:896
	ds_read_b128 v[206:209], v34 offset:912
	ds_read_b128 v[210:213], v34 offset:928
	ds_read_b128 v[214:217], v34 offset:944
	ds_read_b128 v[218:221], v34 offset:960
	ds_read_b128 v[222:225], v34 offset:976
	ds_read_b128 v[226:229], v34 offset:992
	ds_read_b128 v[230:233], v34 offset:1008
	s_waitcnt lgkmcnt(0)
	global_load_dword v28, v[28:29], off offset:2048
	s_waitcnt vmcnt(16)
	v_lshlrev_b32_e32 v32, 16, v36
	v_and_b32_e32 v33, 0xffff0000, v36
	v_lshlrev_b32_e32 v56, 16, v37
	v_and_b32_e32 v57, 0xffff0000, v37
	v_lshlrev_b32_e32 v88, 16, v38
	v_and_b32_e32 v89, 0xffff0000, v38
	v_lshlrev_b32_e32 v90, 16, v39
	v_and_b32_e32 v91, 0xffff0000, v39
	s_waitcnt lgkmcnt(1)
; #define LAS __attribute__((address_space(3)))
; __device__ __forceinline__ float dot4(f32x4 a, f32x4 b) { return (a[0] * b[0] + a[1] * b[1]) + (a[2] * b[2] + a[3] * b[3]); }
; __device__ __forceinline__ void unpack8(u32x4 w, f32x4& a, f32x4& b) { a = (f32x4){bflo(w.x), bfhi(w.x), bflo(w.y), bfhi(w.y)}; b = (f32x4){bflo(w.z), bfhi(w.z), bflo(w.w), bfhi(w.w)}; }
; __device__ __forceinline__ void sample_mix_even(Frame& F0, int j, int b) {
;     ...
;         for (int hb = 0; hb < 2; ++hb) {
;             u32x4 pr[16];
; #pragma unroll
;             for (int i = 0; i < 16; ++i) pr[i] = *(const u32x4*)(pm + hb * 128 + i * 8);
; #pragma unroll
;             for (int i = 0; i < 16; ++i) { f32x4 p0, p1; unpack8(pr[i], p0, p1); const LAS float* q = pg + hb * 128 + i * 8; a += dot4(p0, *(const LAS f32x4*)q) + dot4(p1, *(const LAS f32x4*)(q + 4)); }
;         }
	v_mul_f32_e32 v33, v103, v33
	v_fmac_f32_e32 v33, v102, v32
	v_mul_f32_e32 v32, v105, v57
	v_fmac_f32_e32 v32, v104, v56
	v_add_f32_e32 v32, v33, v32
	s_waitcnt lgkmcnt(0)
	v_mul_f32_e32 v33, v107, v89
	v_fmac_f32_e32 v33, v106, v88
	v_mul_f32_e32 v36, v109, v91
	v_fmac_f32_e32 v36, v108, v90
	v_add_f32_e32 v33, v33, v36
	v_add_f32_e32 v32, v32, v33
	v_add_f32_e32 v32, v35, v32
	s_waitcnt vmcnt(15)
	v_lshlrev_b32_e32 v33, 16, v40
	v_and_b32_e32 v35, 0xffff0000, v40
	v_lshlrev_b32_e32 v56, 16, v41
	v_and_b32_e32 v57, 0xffff0000, v41
	v_lshlrev_b32_e32 v84, 16, v42
	v_and_b32_e32 v85, 0xffff0000, v42
	v_lshlrev_b32_e32 v86, 16, v43
	v_and_b32_e32 v87, 0xffff0000, v43
	s_waitcnt lgkmcnt(1)
	v_mul_f32_e32 v35, v111, v35
	v_fmac_f32_e32 v35, v110, v33
	v_mul_f32_e32 v33, v113, v57
	v_fmac_f32_e32 v33, v112, v56
	v_add_f32_e32 v33, v35, v33
	s_waitcnt lgkmcnt(0)
	v_mul_f32_e32 v35, v115, v85
	v_mul_f32_e32 v36, v117, v87
	v_fmac_f32_e32 v35, v114, v84
	v_fmac_f32_e32 v36, v116, v86
	v_add_f32_e32 v35, v35, v36
	v_add_f32_e32 v33, v33, v35
	s_waitcnt vmcnt(14)
	v_and_b32_e32 v35, 0xffff0000, v44
	v_add_f32_e32 v32, v32, v33
	v_lshlrev_b32_e32 v33, 16, v44
	v_lshlrev_b32_e32 v44, 16, v45
	v_and_b32_e32 v45, 0xffff0000, v45
	s_waitcnt lgkmcnt(1)
	v_mul_f32_e32 v35, v119, v35
	v_fmac_f32_e32 v35, v118, v33
	v_mul_f32_e32 v33, v121, v45
	v_lshlrev_b32_e32 v56, 16, v46
	v_and_b32_e32 v46, 0xffff0000, v46
	v_lshlrev_b32_e32 v57, 16, v47
	v_and_b32_e32 v47, 0xffff0000, v47
	v_fmac_f32_e32 v33, v120, v44
	v_add_f32_e32 v33, v35, v33
	s_waitcnt lgkmcnt(0)
	v_mul_f32_e32 v35, v123, v46
	v_mul_f32_e32 v36, v125, v47
	v_fmac_f32_e32 v35, v122, v56
	v_fmac_f32_e32 v36, v124, v57
	v_add_f32_e32 v35, v35, v36
	v_add_f32_e32 v33, v33, v35
	s_waitcnt vmcnt(13)
	v_and_b32_e32 v35, 0xffff0000, v48
	v_add_f32_e32 v32, v32, v33
	v_lshlrev_b32_e32 v33, 16, v48
	v_and_b32_e32 v45, 0xffff0000, v49
	s_waitcnt lgkmcnt(1)
	v_mul_f32_e32 v35, v127, v35
	v_lshlrev_b32_e32 v44, 16, v49
	v_fmac_f32_e32 v35, v126, v33
	v_mul_f32_e32 v33, v129, v45
	v_and_b32_e32 v47, 0xffff0000, v50
	v_and_b32_e32 v49, 0xffff0000, v51
	v_fmac_f32_e32 v33, v128, v44
	v_lshlrev_b32_e32 v46, 16, v50
	v_lshlrev_b32_e32 v48, 16, v51
	v_add_f32_e32 v33, v35, v33
	s_waitcnt lgkmcnt(0)
	v_mul_f32_e32 v35, v131, v47
	v_mul_f32_e32 v36, v133, v49
	v_fmac_f32_e32 v35, v130, v46
	v_fmac_f32_e32 v36, v132, v48
	v_add_f32_e32 v35, v35, v36
	v_add_f32_e32 v33, v33, v35
	s_waitcnt vmcnt(9)
	v_and_b32_e32 v35, 0xffff0000, v68
	v_add_f32_e32 v32, v32, v33
	v_lshlrev_b32_e32 v33, 16, v68
	v_and_b32_e32 v45, 0xffff0000, v69
	s_waitcnt lgkmcnt(1)
	v_mul_f32_e32 v35, v135, v35
	v_lshlrev_b32_e32 v44, 16, v69
	v_fmac_f32_e32 v35, v134, v33
	v_mul_f32_e32 v33, v137, v45
	v_and_b32_e32 v47, 0xffff0000, v70
	v_and_b32_e32 v49, 0xffff0000, v71
	v_fmac_f32_e32 v33, v136, v44
	v_lshlrev_b32_e32 v46, 16, v70
	v_lshlrev_b32_e32 v48, 16, v71
	v_add_f32_e32 v33, v35, v33
	s_waitcnt lgkmcnt(0)
	v_mul_f32_e32 v35, v139, v47
	v_mul_f32_e32 v36, v141, v49
	v_fmac_f32_e32 v35, v138, v46
	v_fmac_f32_e32 v36, v140, v48
	v_add_f32_e32 v35, v35, v36
	v_add_f32_e32 v33, v33, v35
	v_and_b32_e32 v35, 0xffff0000, v64
	v_add_f32_e32 v32, v32, v33
	v_lshlrev_b32_e32 v33, 16, v64
	v_and_b32_e32 v45, 0xffff0000, v65
	s_waitcnt lgkmcnt(1)
	v_mul_f32_e32 v35, v143, v35
	v_lshlrev_b32_e32 v44, 16, v65
	v_fmac_f32_e32 v35, v142, v33
	v_mul_f32_e32 v33, v145, v45
	v_and_b32_e32 v47, 0xffff0000, v66
	v_and_b32_e32 v49, 0xffff0000, v67
	v_fmac_f32_e32 v33, v144, v44
	v_lshlrev_b32_e32 v46, 16, v66
	v_lshlrev_b32_e32 v48, 16, v67
	v_add_f32_e32 v33, v35, v33
	s_waitcnt lgkmcnt(0)
	v_mul_f32_e32 v35, v147, v47
	v_mul_f32_e32 v36, v149, v49
	v_fmac_f32_e32 v35, v146, v46
	v_fmac_f32_e32 v36, v148, v48
	v_add_f32_e32 v35, v35, v36
	v_add_f32_e32 v33, v33, v35
	v_and_b32_e32 v35, 0xffff0000, v60
	v_add_f32_e32 v32, v32, v33
	v_lshlrev_b32_e32 v33, 16, v60
	v_and_b32_e32 v45, 0xffff0000, v61
	s_waitcnt lgkmcnt(1)
	v_mul_f32_e32 v35, v151, v35
	v_lshlrev_b32_e32 v44, 16, v61
	v_fmac_f32_e32 v35, v150, v33
	v_mul_f32_e32 v33, v153, v45
	v_and_b32_e32 v47, 0xffff0000, v62
	v_and_b32_e32 v49, 0xffff0000, v63
	v_fmac_f32_e32 v33, v152, v44
	v_lshlrev_b32_e32 v46, 16, v62
	v_lshlrev_b32_e32 v48, 16, v63
	v_add_f32_e32 v33, v35, v33
	s_waitcnt lgkmcnt(0)
	v_mul_f32_e32 v35, v155, v47
	v_mul_f32_e32 v36, v157, v49
	v_fmac_f32_e32 v35, v154, v46
	v_fmac_f32_e32 v36, v156, v48
	v_add_f32_e32 v35, v35, v36
	v_add_f32_e32 v33, v33, v35
	v_and_b32_e32 v35, 0xffff0000, v52
	v_add_f32_e32 v32, v32, v33
	v_lshlrev_b32_e32 v33, 16, v52
	v_and_b32_e32 v45, 0xffff0000, v53
	s_waitcnt lgkmcnt(1)
	v_mul_f32_e32 v35, v159, v35
	v_lshlrev_b32_e32 v44, 16, v53
	v_fmac_f32_e32 v35, v158, v33
	v_mul_f32_e32 v33, v161, v45
	v_and_b32_e32 v47, 0xffff0000, v54
	v_and_b32_e32 v49, 0xffff0000, v55
	v_fmac_f32_e32 v33, v160, v44
	v_lshlrev_b32_e32 v46, 16, v54
	v_lshlrev_b32_e32 v48, 16, v55
	v_add_f32_e32 v33, v35, v33
	s_waitcnt lgkmcnt(0)
	v_mul_f32_e32 v35, v163, v47
	v_mul_f32_e32 v36, v165, v49
	v_fmac_f32_e32 v35, v162, v46
	v_fmac_f32_e32 v36, v164, v48
	v_add_f32_e32 v35, v35, v36
	v_add_f32_e32 v33, v33, v35
	s_waitcnt vmcnt(5)
	v_and_b32_e32 v35, 0xffff0000, v80
	v_add_f32_e32 v32, v32, v33
	v_lshlrev_b32_e32 v33, 16, v80
	v_and_b32_e32 v45, 0xffff0000, v81
	s_waitcnt lgkmcnt(1)
	v_mul_f32_e32 v35, v167, v35
	v_lshlrev_b32_e32 v44, 16, v81
	v_fmac_f32_e32 v35, v166, v33
	v_mul_f32_e32 v33, v169, v45
	v_and_b32_e32 v47, 0xffff0000, v82
	v_and_b32_e32 v49, 0xffff0000, v83
	v_fmac_f32_e32 v33, v168, v44
	v_lshlrev_b32_e32 v46, 16, v82
	v_lshlrev_b32_e32 v48, 16, v83
	v_add_f32_e32 v33, v35, v33
	s_waitcnt lgkmcnt(0)
; __device__ __forceinline__ unsigned cvt_pk_bf16(float lo, float hi) { const f32x2cv v = {lo, hi}; return __builtin_bit_cast(unsigned, __builtin_convertvector(v, bf16x2cv)); }
; #define LAS __attribute__((address_space(3)))
; __device__ __forceinline__ float silu_f(float x) { return x * __builtin_amdgcn_rcpf(1.f + __builtin_amdgcn_exp2f(-1.4426950408889634f * x)); }
; __device__ __forceinline__ float dot4(f32x4 a, f32x4 b) { return (a[0] * b[0] + a[1] * b[1]) + (a[2] * b[2] + a[3] * b[3]); }
; __device__ __forceinline__ void unpack8(u32x4 w, f32x4& a, f32x4& b) { a = (f32x4){bflo(w.x), bfhi(w.x), bflo(w.y), bfhi(w.y)}; b = (f32x4){bflo(w.z), bfhi(w.z), bflo(w.w), bfhi(w.w)}; }
; __device__ __forceinline__ void sample_mix_even(Frame& F0, int j, int b) {
;     ...
;         for (int hb = 0; hb < 2; ++hb) {
;             u32x4 pr[16];
; #pragma unroll
;             for (int i = 0; i < 16; ++i) pr[i] = *(const u32x4*)(pm + hb * 128 + i * 8);
; #pragma unroll
;             for (int i = 0; i < 16; ++i) { f32x4 p0, p1; unpack8(pr[i], p0, p1); const LAS float* q = pg + hb * 128 + i * 8; a += dot4(p0, *(const LAS f32x4*)q) + dot4(p1, *(const LAS f32x4*)(q + 4)); }
;         }
;         const float ya = a * FIN(12)[j * 1024 + d] * silu_f(z[1024 + d]);
;         const float vn = vv[k] * rv * FIN(15)[j * 1024 + d];
;         F.out[O_SGUV + (size_t)(j * 128 + b) * 1024 + d] = vn;
;         const float mixed = FIN(13)[(size_t)(j * 4 + g) * 16384] * vn + FIN(14)[(j * 4 + g) * 128];
;         const float yb = z[2048 + d] * mixed * silu_f(z[4096 + d]);
;         ((bf16_t*)(F.ws + WS_SA2))[(size_t)b * 2048 + d] = (bf16_t)(cvt_pk_bf16(ya, 0.f) & 0xffffu); ((bf16_t*)(F.ws + WS_SA2))[(size_t)b * 2048 + 1024 + d] = (bf16_t)(cvt_pk_bf16(yb, 0.f) & 0xffffu);
;     }
;     __syncthreads();
	v_mul_f32_e32 v35, v171, v47
	v_mul_f32_e32 v36, v173, v49
	v_fmac_f32_e32 v35, v170, v46
	v_fmac_f32_e32 v36, v172, v48
	v_add_f32_e32 v35, v35, v36
	v_add_f32_e32 v33, v33, v35
	v_and_b32_e32 v35, 0xffff0000, v76
	v_add_f32_e32 v32, v32, v33
	v_lshlrev_b32_e32 v33, 16, v76
	v_and_b32_e32 v45, 0xffff0000, v77
	s_waitcnt lgkmcnt(1)
	v_mul_f32_e32 v35, v175, v35
	v_lshlrev_b32_e32 v44, 16, v77
	v_fmac_f32_e32 v35, v174, v33
	v_mul_f32_e32 v33, v177, v45
	v_and_b32_e32 v47, 0xffff0000, v78
	v_and_b32_e32 v49, 0xffff0000, v79
	v_fmac_f32_e32 v33, v176, v44
	v_lshlrev_b32_e32 v46, 16, v78
	v_lshlrev_b32_e32 v48, 16, v79
	v_add_f32_e32 v29, v35, v33
	s_waitcnt lgkmcnt(1)
	v_mul_f32_e32 v33, v179, v47
	v_mul_f32_e32 v35, v181, v49
	v_fmac_f32_e32 v33, v178, v46
	v_fmac_f32_e32 v35, v180, v48
	v_add_f32_e32 v33, v33, v35
	v_add_f32_e32 v29, v29, v33
	v_and_b32_e32 v33, 0xffff0000, v72
	v_add_f32_e32 v29, v32, v29
	v_lshlrev_b32_e32 v32, 16, v72
	v_and_b32_e32 v44, 0xffff0000, v73
	s_waitcnt lgkmcnt(1)
	v_mul_f32_e32 v33, v183, v33
	v_lshlrev_b32_e32 v35, 16, v73
	v_fmac_f32_e32 v33, v182, v32
	v_mul_f32_e32 v32, v185, v44
	v_and_b32_e32 v46, 0xffff0000, v74
	v_and_b32_e32 v48, 0xffff0000, v75
	v_fmac_f32_e32 v32, v184, v35
	v_lshlrev_b32_e32 v45, 16, v74
	v_lshlrev_b32_e32 v47, 16, v75
	v_add_f32_e32 v32, v33, v32
	s_waitcnt lgkmcnt(0)
	v_mul_f32_e32 v33, v187, v46
	v_mul_f32_e32 v35, v189, v48
	v_fmac_f32_e32 v33, v186, v45
	v_fmac_f32_e32 v35, v188, v47
	v_add_f32_e32 v33, v33, v35
	v_add_f32_e32 v32, v32, v33
	v_add_f32_e32 v29, v29, v32
	v_lshlrev_b32_e32 v32, 16, v16
	v_and_b32_e32 v16, 0xffff0000, v16
	v_lshlrev_b32_e32 v33, 16, v17
	v_and_b32_e32 v35, 0xffff0000, v17
	v_lshlrev_b32_e32 v40, 16, v18
	v_and_b32_e32 v41, 0xffff0000, v18
	v_lshlrev_b32_e32 v42, 16, v19
	v_and_b32_e32 v43, 0xffff0000, v19
	s_waitcnt lgkmcnt(0)
	v_mul_f32_e32 v37, v191, v16
	v_fmac_f32_e32 v37, v190, v32
	v_mul_f32_e32 v32, v193, v35
	v_fmac_f32_e32 v32, v192, v33
	v_add_f32_e32 v32, v37, v32
	s_waitcnt lgkmcnt(0)
	v_mul_f32_e32 v17, v195, v41
	v_fmac_f32_e32 v17, v194, v40
	v_mul_f32_e32 v16, v197, v43
	v_fmac_f32_e32 v16, v196, v42
	v_add_f32_e32 v16, v17, v16
	s_waitcnt vmcnt(1)
	v_lshlrev_b32_e32 v17, 16, v12
	v_and_b32_e32 v12, 0xffff0000, v12
	v_lshlrev_b32_e32 v18, 16, v13
	v_and_b32_e32 v13, 0xffff0000, v13
	s_waitcnt lgkmcnt(1)
	v_mul_f32_e32 v12, v203, v12
	v_mul_f32_e32 v13, v205, v13
	v_add_f32_e32 v16, v32, v16
	v_lshlrev_b32_e32 v19, 16, v14
	v_and_b32_e32 v14, 0xffff0000, v14
	v_and_b32_e32 v32, 0xffff0000, v15
	v_fmac_f32_e32 v12, v202, v17
	v_fmac_f32_e32 v13, v204, v18
	v_add_f32_e32 v16, v29, v16
	v_lshlrev_b32_e32 v29, 16, v15
	v_add_f32_e32 v15, v12, v13
	s_waitcnt lgkmcnt(0)
	v_mul_f32_e32 v12, v207, v14
	v_mul_f32_e32 v13, v209, v32
	v_fmac_f32_e32 v12, v206, v19
	v_fmac_f32_e32 v13, v208, v29
	v_add_f32_e32 v17, v12, v13
	v_add_co_u32_e32 v12, vcc, s70, v24
	v_mul_f32_e32 v19, v58, v59
	s_nop 0
	v_addc_co_u32_e32 v13, vcc, 0, v25, vcc
	s_waitcnt vmcnt(0)
	v_mul_f32_e32 v19, v19, v28
	v_add_co_u32_e32 v24, vcc, s94, v24
	global_load_dword v14, v[30:31], off offset:2048
	global_load_dword v18, v[12:13], off offset:-4096
	v_addc_co_u32_e32 v25, vcc, 0, v25, vcc
	global_store_dword v[26:27], v19, off offset:2048
	global_load_dword v26, v[24:25], off
	v_lshlrev_b64 v[24:25], 16, v[22:23]
	v_lshlrev_b32_e32 v22, 7, v22
	v_lshl_add_u64 v[24:25], s[6:7], 0, v[24:25]
	v_ashrrev_i32_e32 v23, 31, v22
	v_add_f32_e32 v15, v15, v17
	global_load_dword v17, v[24:25], off
	v_lshl_add_u64 v[22:23], v[22:23], 2, s[8:9]
	global_load_dword v27, v[22:23], off
	s_nop 0
	global_load_dword v12, v[12:13], off
	v_add_f32_e32 v13, v16, v15
	v_lshlrev_b32_e32 v15, 16, v8
	v_and_b32_e32 v8, 0xffff0000, v8
	v_lshlrev_b32_e32 v16, 16, v9
	v_and_b32_e32 v28, 0xffff0000, v9
	v_lshlrev_b32_e32 v29, 16, v10
	v_and_b32_e32 v30, 0xffff0000, v10
	v_lshlrev_b32_e32 v31, 16, v11
	v_and_b32_e32 v32, 0xffff0000, v11
	s_waitcnt lgkmcnt(0)
	v_mul_f32_e32 v23, v211, v8
	v_fmac_f32_e32 v23, v210, v15
	v_mul_f32_e32 v15, v213, v28
	v_fmac_f32_e32 v15, v212, v16
	v_add_f32_e32 v15, v23, v15
	s_waitcnt lgkmcnt(0)
	v_mul_f32_e32 v9, v215, v30
	v_fmac_f32_e32 v9, v214, v29
	v_mul_f32_e32 v8, v217, v32
	v_fmac_f32_e32 v8, v216, v31
	v_add_f32_e32 v8, v9, v8
	v_add_f32_e32 v8, v15, v8
	v_add_f32_e32 v13, v13, v8
	v_lshlrev_b32_e32 v15, 16, v4
	v_and_b32_e32 v4, 0xffff0000, v4
	v_lshlrev_b32_e32 v16, 16, v5
	v_and_b32_e32 v22, 0xffff0000, v5
	v_lshlrev_b32_e32 v23, 16, v6
	v_and_b32_e32 v24, 0xffff0000, v6
	v_lshlrev_b32_e32 v25, 16, v7
	v_and_b32_e32 v28, 0xffff0000, v7
	s_waitcnt lgkmcnt(0)
	v_mul_f32_e32 v9, v219, v4
	v_fmac_f32_e32 v9, v218, v15
	v_mul_f32_e32 v8, v221, v22
	v_fmac_f32_e32 v8, v220, v16
	v_add_f32_e32 v8, v9, v8
	s_waitcnt lgkmcnt(0)
	v_mul_f32_e32 v5, v223, v24
	v_fmac_f32_e32 v5, v222, v23
	v_mul_f32_e32 v4, v225, v28
	v_fmac_f32_e32 v4, v224, v25
	v_add_f32_e32 v4, v5, v4
	v_add_f32_e32 v4, v8, v4
	v_add_f32_e32 v8, v13, v4
	v_lshlrev_b32_e32 v9, 16, v0
	v_and_b32_e32 v0, 0xffff0000, v0
	v_lshlrev_b32_e32 v10, 16, v1
	v_and_b32_e32 v11, 0xffff0000, v1
	v_lshlrev_b32_e32 v13, 16, v2
	v_and_b32_e32 v15, 0xffff0000, v2
	v_lshlrev_b32_e32 v16, 16, v3
	v_and_b32_e32 v22, 0xffff0000, v3
	s_waitcnt lgkmcnt(0)
	v_mul_f32_e32 v5, v227, v0
	v_fmac_f32_e32 v5, v226, v9
	v_mul_f32_e32 v4, v229, v11
	v_fmac_f32_e32 v4, v228, v10
	v_add_f32_e32 v4, v5, v4
	s_waitcnt lgkmcnt(0)
	v_mul_f32_e32 v1, v231, v15
	v_fmac_f32_e32 v1, v230, v13
	v_mul_f32_e32 v0, v233, v22
	v_fmac_f32_e32 v0, v232, v16
	v_add_f32_e32 v0, v1, v0
	v_add_f32_e32 v0, v4, v0
	v_add_f32_e32 v0, v8, v0
	s_waitcnt vmcnt(5)
	v_mul_f32_e32 v3, 0xbfb8aa3b, v18
	v_exp_f32_e32 v3, v3
	v_mul_f32_e32 v0, v14, v0
	s_waitcnt vmcnt(3)
	v_mul_f32_e32 v2, 0xbfb8aa3b, v26
	v_exp_f32_e32 v2, v2
	v_add_f32_e32 v1, 1.0, v3
	v_rcp_f32_e32 v1, v1
	v_add_f32_e32 v2, 1.0, v2
	v_rcp_f32_e32 v2, v2
	v_mul_f32_e32 v1, v18, v1
	s_waitcnt vmcnt(1)
	v_fmac_f32_e32 v27, v19, v17
	v_mul_f32_e32 v0, v0, v1
	s_waitcnt vmcnt(0)
	v_mul_f32_e32 v1, v12, v27
	v_mul_f32_e32 v2, v26, v2
	v_mul_f32_e32 v1, v1, v2
	v_cvt_pk_bf16_f32 v0, v0, s0
	global_store_short v[20:21], v0, off offset:1024
	v_cvt_pk_bf16_f32 v0, v1, s0
	global_store_short v[20:21], v0, off offset:3072
	s_barrier
	s_cbranch_scc0 .LBB0_1609
